# P4 conv+gate section hand-rewritten (DPP folded into FMAs, 5 VALU per conv value, next weights prefetched); attention VALU stream spread 4 per MFMA gap from a5
# speedup vs baseline: 1.0183x; 1.0146x over previous
; #define LAS __attribute__((address_space(3)))
; #define MFMA32(a, b, c) __builtin_amdgcn_mfma_f32_32x32x16_bf16((a), (b), (c), 0, 0, 0)
; __device__ __forceinline__ void attn_phase_fast(LAS unsigned char* lds, const bf16_t* q, const bf16_t* k, const bf16_t* vT, bf16_t* mixed, float lam, const int wave_s) {
;     ...
; #pragma unroll
;             for (int m = 0; m < 2; ++m) {
;                 f32x16 s0, s1;
; #pragma unroll
;                 for (int i = 0; i < 16; ++i) { s0[i] = 0.f; s1[i] = 0.f; }
; #pragma unroll
;                 for (int d0 = 0; d0 < 4; ++d0) {
;                     const int kpos = ((m * 4 + d0) << 5) ^ kxh;
;                     const bf16x8 k0 = *(const LAS bf16x8*)(Kb + kpos), k1 = *(const LAS bf16x8*)(Kb + 32 * KROW + kpos);
;                     const bf16x8 qv = *(const LAS bf16x8*)(Qs + m * 128 + d0 * 32);
;                     s0 = MFMA32(k0, qv, s0); s1 = MFMA32(k1, qv, s1);
;                 }
;                 __builtin_amdgcn_sched_barrier(0);
;                 float ls = 0.f, ls2 = 0.f;
; #pragma unroll
;                 for (int i = 0; i < 16; ++i) { float e0 = __builtin_amdgcn_exp2f(s0[i]), e1 = __builtin_amdgcn_exp2f(s1[i]); asm volatile("" : "+v"(e0), "+v"(e1)); s0[i] = e0; s1[i] = e1; ls += e0; ls2 += e1; }
;                 ls += ls2;
;                 l[m] += ls;
;                 const bf16x8 p0 = packp(s0, 0), p1 = packp(s0, 1), p2 = packp(s1, 0), p3 = packp(s1, 1);
; #pragma unroll
;                 for (int db = 0; db < 4; ++db) {
;                     const LAS unsigned char* vb = Vb + db * 32 * VROW;
;                     const bf16x8 v0 = *(const LAS bf16x8*)(vb + (0 ^ vxh)), v1 = *(const LAS bf16x8*)(vb + (32 ^ vxh)), v2 = *(const LAS bf16x8*)(vb + (64 ^ vxh)), v3 = *(const LAS bf16x8*)(vb + (96 ^ vxh));
;                     o[m][db] = MFMA32(v0, p0, o[m][db]); o[m][db] = MFMA32(v1, p1, o[m][db]); o[m][db] = MFMA32(v2, p2, o[m][db]); o[m][db] = MFMA32(v3, p3, o[m][db]);
;                     if (db == 1) __builtin_amdgcn_sched_barrier(0);
;                 }
.Lattn_skip_tail:
	s_waitcnt lgkmcnt(7)
	v_mfma_f32_32x32x16_bf16 v[128:143], v[144:147], v[180:183], 0
	ds_read_b128 v[216:219], v228 offset:128
	s_waitcnt lgkmcnt(7)
	v_mfma_f32_32x32x16_bf16 v[128:143], v[148:151], v[184:187], v[128:143]
	ds_read_b128 v[220:223], v228 offset:160
	s_waitcnt lgkmcnt(7)
	v_mfma_f32_32x32x16_bf16 v[128:143], v[152:155], v[188:191], v[128:143]
	ds_read_b128 v[224:227], v228 offset:192
	s_waitcnt lgkmcnt(7)
	v_mfma_f32_32x32x16_bf16 v[128:143], v[156:159], v[192:195], v[128:143]
	ds_read_b128 v[234:237], v228 offset:224
	s_waitcnt lgkmcnt(7)
	v_mfma_f32_32x32x16_bf16 v[144:159], v[164:167], v[180:183], 0
	ds_read_b128 v[180:183], v200
	ds_read_b128 v[238:241], v200 offset:8192
	s_nop 6
	v_exp_f32_e32 v128, v128
	v_exp_f32_e32 v129, v129
	v_add_f32_e32 v162, v162, v128
	v_exp_f32_e32 v130, v130
	s_waitcnt lgkmcnt(8)
	v_mfma_f32_32x32x16_bf16 v[144:159], v[168:171], v[184:187], v[144:159]
	ds_read_b128 v[184:187], v201
	ds_read_b128 v[242:245], v201 offset:8192
	v_add_f32_e32 v162, v162, v129
	v_exp_f32_e32 v131, v131
	v_add_f32_e32 v162, v162, v130
	v_cvt_pk_bf16_f32 v128, v128, v129
	s_waitcnt lgkmcnt(9)
	v_mfma_f32_32x32x16_bf16 v[144:159], v[172:175], v[188:191], v[144:159]
	ds_read_b128 v[188:191], v202
	ds_read_b128 v[246:249], v202 offset:8192
	v_exp_f32_e32 v132, v132
	v_add_f32_e32 v162, v162, v131
	v_exp_f32_e32 v133, v133
	v_add_f32_e32 v162, v162, v132
	s_waitcnt lgkmcnt(10)
	v_mfma_f32_32x32x16_bf16 v[144:159], v[212:215], v[192:195], v[144:159]
	ds_read_b128 v[192:195], v203
	ds_read_b128 v[212:215], v203 offset:8192
	v_cvt_pk_bf16_f32 v129, v130, v131
	v_exp_f32_e32 v134, v134
	v_add_f32_e32 v162, v162, v133
	v_exp_f32_e32 v135, v135
	s_waitcnt lgkmcnt(7)
	v_mfma_f32_32x32x16_bf16 v[164:179], v[180:183], v[216:219], 0
	ds_read_b128 v[250:253], v204
	s_add_i32 m0, s22, 0x8000
	s_nop 0
	global_load_lds_dwordx4 v208, s[6:7]
	v_add_f32_e32 v162, v162, v134
	v_cvt_pk_bf16_f32 v130, v132, v133
	v_exp_f32_e32 v136, v136
	v_add_f32_e32 v162, v162, v135
	s_waitcnt lgkmcnt(6)
	v_mfma_f32_32x32x16_bf16 v[164:179], v[184:187], v[220:223], v[164:179]
	s_add_i32 m0, s24, 0x8000
	s_nop 0
	global_load_lds_dwordx4 v209, s[2:3]
	v_exp_f32_e32 v137, v137
	v_add_f32_e32 v162, v162, v136
	v_cvt_pk_bf16_f32 v131, v134, v135
	v_exp_f32_e32 v138, v138
	s_waitcnt lgkmcnt(4)
	v_mfma_f32_32x32x16_bf16 v[164:179], v[188:191], v[224:227], v[164:179]
	s_add_i32 m0, s26, 0x8000
	s_nop 0
	global_load_lds_dwordx4 v210, s[6:7]
	v_add_f32_e32 v162, v162, v137
	v_exp_f32_e32 v139, v139
	v_add_f32_e32 v162, v162, v138
	v_cvt_pk_bf16_f32 v132, v136, v137
	s_waitcnt lgkmcnt(2)
	v_mfma_f32_32x32x16_bf16 v[164:179], v[192:195], v[234:237], v[164:179]
	s_add_i32 m0, s27, 0x8000
	s_nop 0
	global_load_lds_dwordx4 v211, s[2:3]
	s_add_u32 s6, s6, 0x10000
	s_addc_u32 s7, s7, 0
	s_add_u32 s2, s2, 0x80
	s_addc_u32 s3, s3, 0
	v_exp_f32_e32 v140, v140
	v_add_f32_e32 v162, v162, v139
	v_exp_f32_e32 v141, v141
	v_add_f32_e32 v162, v162, v140
	v_mfma_f32_32x32x16_bf16 v[180:195], v[238:241], v[216:219], 0
	ds_read_b128 v[216:219], v204 offset:4096
	ds_read_b128 v[238:241], v204 offset:8192
	v_cvt_pk_bf16_f32 v133, v138, v139
	v_exp_f32_e32 v142, v142
	v_add_f32_e32 v162, v162, v141
	v_exp_f32_e32 v143, v143
	v_mfma_f32_32x32x16_bf16 v[180:195], v[242:245], v[220:223], v[180:195]
	ds_read_b128 v[220:223], v204 offset:12288
	ds_read_b128 v[242:245], v205
	v_add_f32_e32 v162, v162, v142
	v_cvt_pk_bf16_f32 v134, v140, v141
	v_add_f32_e32 v162, v162, v143
	v_cvt_pk_bf16_f32 v135, v142, v143
	v_mfma_f32_32x32x16_bf16 v[180:195], v[246:249], v[224:227], v[180:195]
	ds_read_b128 v[224:227], v205 offset:4096
	ds_read_b128 v[246:249], v205 offset:8192
	v_exp_f32_e32 v144, v144
	v_exp_f32_e32 v145, v145
	v_add_f32_e32 v162, v162, v144
	v_exp_f32_e32 v146, v146
	s_waitcnt lgkmcnt(7)
	v_mfma_f32_32x32x16_bf16 v[180:195], v[212:215], v[234:237], v[180:195]
	ds_read_b128 v[212:215], v205 offset:12288
	ds_read_b128 v[234:237], v206
	v_add_f32_e32 v162, v162, v145
	v_exp_f32_e32 v147, v147
	v_add_f32_e32 v162, v162, v146
	v_cvt_pk_bf16_f32 v136, v144, v145
	s_waitcnt lgkmcnt(8)
	v_mfma_f32_32x32x16_bf16 v[112:127], v[250:253], v[128:131], v[112:127]
	ds_read_b128 v[250:253], v206 offset:4096
	v_exp_f32_e32 v148, v148
	v_add_f32_e32 v162, v162, v147
	v_exp_f32_e32 v149, v149
	v_add_f32_e32 v162, v162, v148
	s_waitcnt lgkmcnt(8)
	v_mfma_f32_32x32x16_bf16 v[80:95], v[216:219], v[128:131], v[80:95]
	ds_read_b128 v[216:219], v206 offset:8192
	v_cvt_pk_bf16_f32 v137, v146, v147
	v_exp_f32_e32 v150, v150
	v_add_f32_e32 v162, v162, v149
	v_exp_f32_e32 v151, v151
	s_waitcnt lgkmcnt(8)
	v_mfma_f32_32x32x16_bf16 v[48:63], v[238:241], v[128:131], v[48:63]
	ds_read_b128 v[238:241], v206 offset:12288
	v_add_f32_e32 v162, v162, v150
	v_cvt_pk_bf16_f32 v138, v148, v149
	v_exp_f32_e32 v152, v152
	v_add_f32_e32 v162, v162, v151
	s_waitcnt lgkmcnt(8)
	v_mfma_f32_32x32x16_bf16 v[16:31], v[220:223], v[128:131], v[16:31]
	ds_read_b128 v[220:223], v207
	v_exp_f32_e32 v153, v153
	v_add_f32_e32 v162, v162, v152
	v_cvt_pk_bf16_f32 v139, v150, v151
	v_exp_f32_e32 v154, v154
	s_waitcnt lgkmcnt(8)
	v_mfma_f32_32x32x16_bf16 v[112:127], v[242:245], v[132:135], v[112:127]
	ds_read_b128 v[242:245], v207 offset:4096
	v_add_f32_e32 v162, v162, v153
	v_exp_f32_e32 v155, v155
	v_add_f32_e32 v162, v162, v154
	v_cvt_pk_bf16_f32 v140, v152, v153
	s_waitcnt lgkmcnt(8)
	v_mfma_f32_32x32x16_bf16 v[80:95], v[224:227], v[132:135], v[80:95]
	ds_read_b128 v[224:227], v207 offset:8192
	v_exp_f32_e32 v156, v156
	v_add_f32_e32 v162, v162, v155
	v_exp_f32_e32 v157, v157
	v_add_f32_e32 v162, v162, v156
	s_waitcnt lgkmcnt(8)
; #define LAS __attribute__((address_space(3)))
; #define MFMA32(a, b, c) __builtin_amdgcn_mfma_f32_32x32x16_bf16((a), (b), (c), 0, 0, 0)
; __device__ __forceinline__ void attn_phase_fast(LAS unsigned char* lds, const bf16_t* q, const bf16_t* k, const bf16_t* vT, bf16_t* mixed, float lam, const int wave_s) {
;     ...
;                 float ls = 0.f, ls2 = 0.f;
; #pragma unroll
;                 for (int i = 0; i < 16; ++i) { float e0 = __builtin_amdgcn_exp2f(s0[i]), e1 = __builtin_amdgcn_exp2f(s1[i]); asm volatile("" : "+v"(e0), "+v"(e1)); s0[i] = e0; s1[i] = e1; ls += e0; ls2 += e1; }
;                 ls += ls2;
;                 l[m] += ls;
;                 const bf16x8 p0 = packp(s0, 0), p1 = packp(s0, 1), p2 = packp(s1, 0), p3 = packp(s1, 1);
; #pragma unroll
;                 for (int db = 0; db < 4; ++db) {
;                     const LAS unsigned char* vb = Vb + db * 32 * VROW;
;                     const bf16x8 v0 = *(const LAS bf16x8*)(vb + (0 ^ vxh)), v1 = *(const LAS bf16x8*)(vb + (32 ^ vxh)), v2 = *(const LAS bf16x8*)(vb + (64 ^ vxh)), v3 = *(const LAS bf16x8*)(vb + (96 ^ vxh));
;                     o[m][db] = MFMA32(v0, p0, o[m][db]); o[m][db] = MFMA32(v1, p1, o[m][db]); o[m][db] = MFMA32(v2, p2, o[m][db]); o[m][db] = MFMA32(v3, p3, o[m][db]);
;                     if (db == 1) __builtin_amdgcn_sched_barrier(0);
;                 }
;                 __builtin_amdgcn_sched_barrier(0);
;             }
;             asm volatile("s_waitcnt vmcnt(0)" ::: "memory");
;             __syncthreads();
	v_mfma_f32_32x32x16_bf16 v[48:63], v[246:249], v[132:135], v[48:63]
	ds_read_b128 v[246:249], v207 offset:12288
	v_cvt_pk_bf16_f32 v141, v154, v155
	v_exp_f32_e32 v158, v158
	v_add_f32_e32 v162, v162, v157
	v_exp_f32_e32 v159, v159
	s_waitcnt lgkmcnt(8)
	v_mfma_f32_32x32x16_bf16 v[16:31], v[212:215], v[132:135], v[16:31]
	ds_read_b128 v[212:215], v204
	v_add_f32_e32 v162, v162, v158
	v_cvt_pk_bf16_f32 v142, v156, v157
	v_add_f32_e32 v162, v162, v159
	v_cvt_pk_bf16_f32 v143, v158, v159
	s_waitcnt lgkmcnt(8)
	v_mfma_f32_32x32x16_bf16 v[112:127], v[234:237], v[136:139], v[112:127]
	ds_read_b128 v[234:237], v204 offset:4096
	v_exp_f32_e32 v164, v164
	v_exp_f32_e32 v165, v165
	v_add_f32_e32 v163, v163, v164
	v_exp_f32_e32 v166, v166
	s_waitcnt lgkmcnt(8)
	v_mfma_f32_32x32x16_bf16 v[80:95], v[250:253], v[136:139], v[80:95]
	ds_read_b128 v[250:253], v204 offset:8192
	v_add_f32_e32 v163, v163, v165
	v_exp_f32_e32 v167, v167
	v_add_f32_e32 v163, v163, v166
	v_cvt_pk_bf16_f32 v164, v164, v165
	s_waitcnt lgkmcnt(8)
	v_mfma_f32_32x32x16_bf16 v[48:63], v[216:219], v[136:139], v[48:63]
	ds_read_b128 v[216:219], v204 offset:12288
	v_exp_f32_e32 v168, v168
	v_add_f32_e32 v163, v163, v167
	v_exp_f32_e32 v169, v169
	v_add_f32_e32 v163, v163, v168
	s_waitcnt lgkmcnt(8)
	v_mfma_f32_32x32x16_bf16 v[16:31], v[238:241], v[136:139], v[16:31]
	ds_read_b128 v[238:241], v205
	v_cvt_pk_bf16_f32 v165, v166, v167
	v_exp_f32_e32 v170, v170
	v_add_f32_e32 v163, v163, v169
	v_exp_f32_e32 v171, v171
	s_waitcnt lgkmcnt(8)
	v_mfma_f32_32x32x16_bf16 v[112:127], v[220:223], v[140:143], v[112:127]
	ds_read_b128 v[220:223], v205 offset:4096
	v_add_f32_e32 v163, v163, v170
	v_cvt_pk_bf16_f32 v166, v168, v169
	v_exp_f32_e32 v172, v172
	v_add_f32_e32 v163, v163, v171
	s_waitcnt lgkmcnt(8)
	v_mfma_f32_32x32x16_bf16 v[80:95], v[242:245], v[140:143], v[80:95]
	ds_read_b128 v[242:245], v205 offset:8192
	v_exp_f32_e32 v173, v173
	v_add_f32_e32 v163, v163, v172
	v_cvt_pk_bf16_f32 v167, v170, v171
	v_exp_f32_e32 v174, v174
	s_waitcnt lgkmcnt(8)
	v_mfma_f32_32x32x16_bf16 v[48:63], v[224:227], v[140:143], v[48:63]
	ds_read_b128 v[224:227], v205 offset:12288
	v_add_f32_e32 v163, v163, v173
	v_exp_f32_e32 v175, v175
	v_add_f32_e32 v163, v163, v174
	v_cvt_pk_bf16_f32 v168, v172, v173
	s_waitcnt lgkmcnt(8)
	v_mfma_f32_32x32x16_bf16 v[16:31], v[246:249], v[140:143], v[16:31]
	ds_read_b128 v[246:249], v206
	v_exp_f32_e32 v176, v176
	v_add_f32_e32 v163, v163, v175
	v_exp_f32_e32 v177, v177
	v_add_f32_e32 v163, v163, v176
	s_waitcnt lgkmcnt(8)
	v_mfma_f32_32x32x16_bf16 v[96:111], v[212:215], v[164:167], v[96:111]
	ds_read_b128 v[212:215], v206 offset:4096
	v_cvt_pk_bf16_f32 v169, v174, v175
	v_exp_f32_e32 v178, v178
	v_add_f32_e32 v163, v163, v177
	v_exp_f32_e32 v179, v179
	s_waitcnt lgkmcnt(8)
	v_mfma_f32_32x32x16_bf16 v[64:79], v[234:237], v[164:167], v[64:79]
	ds_read_b128 v[234:237], v206 offset:8192
	v_add_f32_e32 v163, v163, v178
	v_cvt_pk_bf16_f32 v170, v176, v177
	v_add_f32_e32 v163, v163, v179
	v_cvt_pk_bf16_f32 v171, v178, v179
	s_waitcnt lgkmcnt(8)
	v_mfma_f32_32x32x16_bf16 v[32:47], v[250:253], v[164:167], v[32:47]
	ds_read_b128 v[250:253], v206 offset:12288
	v_exp_f32_e32 v180, v180
	v_exp_f32_e32 v181, v181
	v_add_f32_e32 v163, v163, v180
	v_exp_f32_e32 v182, v182
	s_waitcnt lgkmcnt(8)
	v_mfma_f32_32x32x16_bf16 v[0:15], v[216:219], v[164:167], v[0:15]
	ds_read_b128 v[216:219], v207
	v_add_f32_e32 v163, v163, v181
	v_exp_f32_e32 v183, v183
	v_add_f32_e32 v163, v163, v182
	v_cvt_pk_bf16_f32 v172, v180, v181
	s_waitcnt lgkmcnt(8)
	v_mfma_f32_32x32x16_bf16 v[96:111], v[238:241], v[168:171], v[96:111]
	ds_read_b128 v[238:241], v207 offset:4096
	v_exp_f32_e32 v184, v184
	v_add_f32_e32 v163, v163, v183
	v_exp_f32_e32 v185, v185
	v_add_f32_e32 v163, v163, v184
	s_waitcnt lgkmcnt(8)
	v_mfma_f32_32x32x16_bf16 v[64:79], v[220:223], v[168:171], v[64:79]
	ds_read_b128 v[220:223], v207 offset:8192
	v_cvt_pk_bf16_f32 v173, v182, v183
	v_exp_f32_e32 v186, v186
	v_add_f32_e32 v163, v163, v185
	v_exp_f32_e32 v187, v187
	s_waitcnt lgkmcnt(8)
	v_mfma_f32_32x32x16_bf16 v[32:47], v[242:245], v[168:171], v[32:47]
	ds_read_b128 v[242:245], v207 offset:12288
	v_add_f32_e32 v163, v163, v186
	v_cvt_pk_bf16_f32 v174, v184, v185
	v_exp_f32_e32 v188, v188
	v_add_f32_e32 v163, v163, v187
	s_waitcnt lgkmcnt(8)
	v_mfma_f32_32x32x16_bf16 v[0:15], v[224:227], v[168:171], v[0:15]
	v_exp_f32_e32 v189, v189
	v_add_f32_e32 v163, v163, v188
	v_cvt_pk_bf16_f32 v175, v186, v187
	v_exp_f32_e32 v190, v190
	s_waitcnt lgkmcnt(7)
	v_mfma_f32_32x32x16_bf16 v[96:111], v[246:249], v[172:175], v[96:111]
	v_add_f32_e32 v163, v163, v189
	v_exp_f32_e32 v191, v191
	v_add_f32_e32 v163, v163, v190
	v_cvt_pk_bf16_f32 v176, v188, v189
	s_waitcnt lgkmcnt(6)
	v_mfma_f32_32x32x16_bf16 v[64:79], v[212:215], v[172:175], v[64:79]
	v_exp_f32_e32 v192, v192
	v_add_f32_e32 v163, v163, v191
	v_exp_f32_e32 v193, v193
	v_add_f32_e32 v163, v163, v192
	s_waitcnt lgkmcnt(5)
	v_mfma_f32_32x32x16_bf16 v[32:47], v[234:237], v[172:175], v[32:47]
	v_cvt_pk_bf16_f32 v177, v190, v191
	v_exp_f32_e32 v194, v194
	v_add_f32_e32 v163, v163, v193
	v_exp_f32_e32 v195, v195
	s_waitcnt lgkmcnt(4)
	v_mfma_f32_32x32x16_bf16 v[0:15], v[250:253], v[172:175], v[0:15]
	v_add_f32_e32 v163, v163, v194
	v_cvt_pk_bf16_f32 v178, v192, v193
	v_add_f32_e32 v163, v163, v195
	v_cvt_pk_bf16_f32 v179, v194, v195
	ds_read_b128 v[180:183], v228
	ds_read_b128 v[184:187], v228 offset:32
	ds_read_b128 v[188:191], v228 offset:64
	ds_read_b128 v[192:195], v228 offset:96
	s_waitcnt lgkmcnt(4)
	s_waitcnt vmcnt(0)
	s_barrier
; __device__ __forceinline__ void attn_phase_fast(LAS unsigned char* lds, const bf16_t* q, const bf16_t* k, const bf16_t* vT, bf16_t* mixed, float lam, const int wave_s) {
;     ...
;             if (t + 1 < NT) {
;                 unsigned koff[2], voff[2];
; #pragma unroll
;                 for (int i = 0; i < 2; ++i) {
;                     const int kr = 4 * (2 * wid + i) + (ln >> 4), kc = (ln & 15) ^ (kr & 15); koff[i] = (unsigned)(kr * 512 + kc * 8) * 2u;
;                     const int vd = 8 * (2 * wid + i) + (ln >> 3), vc = (ln & 7) ^ ((vd >> 1) & 7); voff[i] = (unsigned)(vd * MTOK + vc * 8) * 2u;
;                 }
;                 ATT_DMA(nb, Kg + (size_t)(t + 1) * 64 * 512, Vg + (t + 1) * 64);
;             }
;             const LAS unsigned char* Qs = lds + 2 * ABUF + wid * (32 * QROW) + r32 * QROW + hi * 16;
;             int kxh = (kx >> 1) << 5, vxh = (vx >> 1) << 5, kq = cb + r32 * KROW + ((hi ^ (kx & 1)) << 4), vq = cb + KBUF + r32 * VROW + ((hi ^ (vx & 1)) << 4);
;             asm volatile("" : "+v"(kxh), "+v"(vxh), "+v"(kq), "+v"(vq));
;             const LAS unsigned char* Kb = lds + kq;
;             const LAS unsigned char* Vb = lds + vq;
; #pragma unroll
;             for (int m = 0; m < 2; ++m) {
;                 f32x16 s0, s1;
; #pragma unroll
;                 for (int i = 0; i < 16; ++i) { s0[i] = 0.f; s1[i] = 0.f; }
; #pragma unroll
;                 for (int d0 = 0; d0 < 4; ++d0) {
;                     const int kpos = ((m * 4 + d0) << 5) ^ kxh;
;                     const bf16x8 k0 = *(const LAS bf16x8*)(Kb + kpos), k1 = *(const LAS bf16x8*)(Kb + 32 * KROW + kpos);
;                     const bf16x8 qv = *(const LAS bf16x8*)(Qs + m * 128 + d0 * 32);
;                     s0 = MFMA32(k0, qv, s0); s1 = MFMA32(k1, qv, s1);
;                 }
;                 __builtin_amdgcn_sched_barrier(0);
;                 float ls = 0.f, ls2 = 0.f;
; #pragma unroll
;                 for (int i = 0; i < 16; ++i) { float e0 = __builtin_amdgcn_exp2f(s0[i]), e1 = __builtin_amdgcn_exp2f(s1[i]); asm volatile("" : "+v"(e0), "+v"(e1)); s0[i] = e0; s1[i] = e1; ls += e0; ls2 += e1; }
;                 ls += ls2;
;                 l[m] += ls;
;                 const bf16x8 p0 = packp(s0, 0), p1 = packp(s0, 1), p2 = packp(s1, 0), p3 = packp(s1, 1);
; #pragma unroll
;                 for (int db = 0; db < 4; ++db) {
	ds_read_b128 v[144:147], v196 offset:32768
	ds_read_b128 v[148:151], v197 offset:32768
	ds_read_b128 v[152:155], v198 offset:32768
	ds_read_b128 v[156:159], v199 offset:32768
	ds_read_b128 v[164:167], v196 offset:40960
	ds_read_b128 v[168:171], v197 offset:40960
	ds_read_b128 v[172:175], v198 offset:40960
	ds_read_b128 v[212:215], v199 offset:40960
	v_mfma_f32_32x32x16_bf16 v[96:111], v[216:219], v[176:179], v[96:111]
	v_mfma_f32_32x32x16_bf16 v[64:79], v[238:241], v[176:179], v[64:79]
	v_mfma_f32_32x32x16_bf16 v[32:47], v[220:223], v[176:179], v[32:47]
	v_mfma_f32_32x32x16_bf16 v[0:15], v[242:245], v[176:179], v[0:15]
	s_waitcnt lgkmcnt(7)
	v_mfma_f32_32x32x16_bf16 v[128:143], v[144:147], v[180:183], 0
	ds_read_b128 v[216:219], v228 offset:128
	s_waitcnt lgkmcnt(7)
	v_mfma_f32_32x32x16_bf16 v[128:143], v[148:151], v[184:187], v[128:143]
	ds_read_b128 v[220:223], v228 offset:160
	s_waitcnt lgkmcnt(7)
	v_mfma_f32_32x32x16_bf16 v[128:143], v[152:155], v[188:191], v[128:143]
	ds_read_b128 v[224:227], v228 offset:192
	s_waitcnt lgkmcnt(7)
	v_mfma_f32_32x32x16_bf16 v[128:143], v[156:159], v[192:195], v[128:143]
	ds_read_b128 v[234:237], v228 offset:224
	s_waitcnt lgkmcnt(7)
	v_mfma_f32_32x32x16_bf16 v[144:159], v[164:167], v[180:183], 0
	ds_read_b128 v[180:183], v200 offset:32768
	ds_read_b128 v[238:241], v200 offset:40960
	s_nop 6
	v_exp_f32_e32 v128, v128
	v_exp_f32_e32 v129, v129
	v_add_f32_e32 v162, v162, v128
	v_exp_f32_e32 v130, v130
	s_waitcnt lgkmcnt(8)
	v_mfma_f32_32x32x16_bf16 v[144:159], v[168:171], v[184:187], v[144:159]
	ds_read_b128 v[184:187], v201 offset:32768
	ds_read_b128 v[242:245], v201 offset:40960
	v_add_f32_e32 v162, v162, v129
	v_exp_f32_e32 v131, v131
	v_add_f32_e32 v162, v162, v130
	v_cvt_pk_bf16_f32 v128, v128, v129
	s_waitcnt lgkmcnt(9)
	v_mfma_f32_32x32x16_bf16 v[144:159], v[172:175], v[188:191], v[144:159]
	ds_read_b128 v[188:191], v202 offset:32768
	ds_read_b128 v[246:249], v202 offset:40960
	v_exp_f32_e32 v132, v132
	v_add_f32_e32 v162, v162, v131
	v_exp_f32_e32 v133, v133
	v_add_f32_e32 v162, v162, v132
	s_waitcnt lgkmcnt(10)
	v_mfma_f32_32x32x16_bf16 v[144:159], v[212:215], v[192:195], v[144:159]
	ds_read_b128 v[192:195], v203 offset:32768
	ds_read_b128 v[212:215], v203 offset:40960
	v_cvt_pk_bf16_f32 v129, v130, v131
	v_exp_f32_e32 v134, v134
	v_add_f32_e32 v162, v162, v133
	v_exp_f32_e32 v135, v135
	s_waitcnt lgkmcnt(7)
	v_mfma_f32_32x32x16_bf16 v[164:179], v[180:183], v[216:219], 0
	ds_read_b128 v[250:253], v204 offset:32768
	s_mov_b32 m0, s22
	s_nop 0
	global_load_lds_dwordx4 v208, s[6:7]
	v_add_f32_e32 v162, v162, v134
	v_cvt_pk_bf16_f32 v130, v132, v133
	v_exp_f32_e32 v136, v136
	v_add_f32_e32 v162, v162, v135
	s_waitcnt lgkmcnt(6)
	v_mfma_f32_32x32x16_bf16 v[164:179], v[184:187], v[220:223], v[164:179]
	s_mov_b32 m0, s24
	s_nop 0
	global_load_lds_dwordx4 v209, s[2:3]
	v_exp_f32_e32 v137, v137
	v_add_f32_e32 v162, v162, v136
	v_cvt_pk_bf16_f32 v131, v134, v135
	v_exp_f32_e32 v138, v138
	s_waitcnt lgkmcnt(4)
	v_mfma_f32_32x32x16_bf16 v[164:179], v[188:191], v[224:227], v[164:179]
	s_mov_b32 m0, s26
	s_nop 0
	global_load_lds_dwordx4 v210, s[6:7]
	v_add_f32_e32 v162, v162, v137
	v_exp_f32_e32 v139, v139
	v_add_f32_e32 v162, v162, v138
	v_cvt_pk_bf16_f32 v132, v136, v137
	s_waitcnt lgkmcnt(2)
	v_mfma_f32_32x32x16_bf16 v[164:179], v[192:195], v[234:237], v[164:179]
	s_mov_b32 m0, s27
	s_nop 0
	global_load_lds_dwordx4 v211, s[2:3]
	s_add_u32 s6, s6, 0x10000
	s_addc_u32 s7, s7, 0
	s_add_u32 s2, s2, 0x80
	s_addc_u32 s3, s3, 0
	v_exp_f32_e32 v140, v140
	v_add_f32_e32 v162, v162, v139
	v_exp_f32_e32 v141, v141
	v_add_f32_e32 v162, v162, v140
	v_mfma_f32_32x32x16_bf16 v[180:195], v[238:241], v[216:219], 0
	ds_read_b128 v[216:219], v204 offset:36864
	ds_read_b128 v[238:241], v204 offset:40960
	v_cvt_pk_bf16_f32 v133, v138, v139
	v_exp_f32_e32 v142, v142
	v_add_f32_e32 v162, v162, v141
	v_exp_f32_e32 v143, v143
	v_mfma_f32_32x32x16_bf16 v[180:195], v[242:245], v[220:223], v[180:195]
	ds_read_b128 v[220:223], v204 offset:45056
	ds_read_b128 v[242:245], v205 offset:32768
	v_add_f32_e32 v162, v162, v142
	v_cvt_pk_bf16_f32 v134, v140, v141
	v_add_f32_e32 v162, v162, v143
	v_cvt_pk_bf16_f32 v135, v142, v143
	v_mfma_f32_32x32x16_bf16 v[180:195], v[246:249], v[224:227], v[180:195]
	ds_read_b128 v[224:227], v205 offset:36864
	ds_read_b128 v[246:249], v205 offset:40960
	v_exp_f32_e32 v144, v144
	v_exp_f32_e32 v145, v145
	v_add_f32_e32 v162, v162, v144
	v_exp_f32_e32 v146, v146
	s_waitcnt lgkmcnt(7)
	v_mfma_f32_32x32x16_bf16 v[180:195], v[212:215], v[234:237], v[180:195]
	ds_read_b128 v[212:215], v205 offset:45056
	ds_read_b128 v[234:237], v206 offset:32768
	v_add_f32_e32 v162, v162, v145
	v_exp_f32_e32 v147, v147
	v_add_f32_e32 v162, v162, v146
	v_cvt_pk_bf16_f32 v136, v144, v145
	s_waitcnt lgkmcnt(8)
	v_mfma_f32_32x32x16_bf16 v[112:127], v[250:253], v[128:131], v[112:127]
	ds_read_b128 v[250:253], v206 offset:36864
	v_exp_f32_e32 v148, v148
	v_add_f32_e32 v162, v162, v147
	v_exp_f32_e32 v149, v149
	v_add_f32_e32 v162, v162, v148
	s_waitcnt lgkmcnt(8)
	v_mfma_f32_32x32x16_bf16 v[80:95], v[216:219], v[128:131], v[80:95]
	ds_read_b128 v[216:219], v206 offset:40960
	v_cvt_pk_bf16_f32 v137, v146, v147
	v_exp_f32_e32 v150, v150
	v_add_f32_e32 v162, v162, v149
	v_exp_f32_e32 v151, v151
	s_waitcnt lgkmcnt(8)
	v_mfma_f32_32x32x16_bf16 v[48:63], v[238:241], v[128:131], v[48:63]
	ds_read_b128 v[238:241], v206 offset:45056
	v_add_f32_e32 v162, v162, v150
	v_cvt_pk_bf16_f32 v138, v148, v149
	v_exp_f32_e32 v152, v152
	v_add_f32_e32 v162, v162, v151
	s_waitcnt lgkmcnt(8)
; #define LAS __attribute__((address_space(3)))
; #define MFMA32(a, b, c) __builtin_amdgcn_mfma_f32_32x32x16_bf16((a), (b), (c), 0, 0, 0)
; __device__ __forceinline__ void attn_phase_fast(LAS unsigned char* lds, const bf16_t* q, const bf16_t* k, const bf16_t* vT, bf16_t* mixed, float lam, const int wave_s) {
;     ...
;                 float ls = 0.f, ls2 = 0.f;
; #pragma unroll
;                 for (int i = 0; i < 16; ++i) { float e0 = __builtin_amdgcn_exp2f(s0[i]), e1 = __builtin_amdgcn_exp2f(s1[i]); asm volatile("" : "+v"(e0), "+v"(e1)); s0[i] = e0; s1[i] = e1; ls += e0; ls2 += e1; }
;                 ls += ls2;
;                 l[m] += ls;
;                 const bf16x8 p0 = packp(s0, 0), p1 = packp(s0, 1), p2 = packp(s1, 0), p3 = packp(s1, 1);
; #pragma unroll
;                 for (int db = 0; db < 4; ++db) {
;                     const LAS unsigned char* vb = Vb + db * 32 * VROW;
;                     const bf16x8 v0 = *(const LAS bf16x8*)(vb + (0 ^ vxh)), v1 = *(const LAS bf16x8*)(vb + (32 ^ vxh)), v2 = *(const LAS bf16x8*)(vb + (64 ^ vxh)), v3 = *(const LAS bf16x8*)(vb + (96 ^ vxh));
;                     o[m][db] = MFMA32(v0, p0, o[m][db]); o[m][db] = MFMA32(v1, p1, o[m][db]); o[m][db] = MFMA32(v2, p2, o[m][db]); o[m][db] = MFMA32(v3, p3, o[m][db]);
;                     if (db == 1) __builtin_amdgcn_sched_barrier(0);
;                 }
;                 __builtin_amdgcn_sched_barrier(0);
;             }
;             asm volatile("s_waitcnt vmcnt(0)" ::: "memory");
;             __syncthreads();
	v_mfma_f32_32x32x16_bf16 v[16:31], v[220:223], v[128:131], v[16:31]
	ds_read_b128 v[220:223], v207 offset:32768
	v_exp_f32_e32 v153, v153
	v_add_f32_e32 v162, v162, v152
	v_cvt_pk_bf16_f32 v139, v150, v151
	v_exp_f32_e32 v154, v154
	s_waitcnt lgkmcnt(8)
	v_mfma_f32_32x32x16_bf16 v[112:127], v[242:245], v[132:135], v[112:127]
	ds_read_b128 v[242:245], v207 offset:36864
	v_add_f32_e32 v162, v162, v153
	v_exp_f32_e32 v155, v155
	v_add_f32_e32 v162, v162, v154
	v_cvt_pk_bf16_f32 v140, v152, v153
	s_waitcnt lgkmcnt(8)
	v_mfma_f32_32x32x16_bf16 v[80:95], v[224:227], v[132:135], v[80:95]
	ds_read_b128 v[224:227], v207 offset:40960
	v_exp_f32_e32 v156, v156
	v_add_f32_e32 v162, v162, v155
	v_exp_f32_e32 v157, v157
	v_add_f32_e32 v162, v162, v156
	s_waitcnt lgkmcnt(8)
	v_mfma_f32_32x32x16_bf16 v[48:63], v[246:249], v[132:135], v[48:63]
	ds_read_b128 v[246:249], v207 offset:45056
	v_cvt_pk_bf16_f32 v141, v154, v155
	v_exp_f32_e32 v158, v158
	v_add_f32_e32 v162, v162, v157
	v_exp_f32_e32 v159, v159
	s_waitcnt lgkmcnt(8)
	v_mfma_f32_32x32x16_bf16 v[16:31], v[212:215], v[132:135], v[16:31]
	ds_read_b128 v[212:215], v204 offset:32768
	v_add_f32_e32 v162, v162, v158
	v_cvt_pk_bf16_f32 v142, v156, v157
	v_add_f32_e32 v162, v162, v159
	v_cvt_pk_bf16_f32 v143, v158, v159
	s_waitcnt lgkmcnt(8)
	v_mfma_f32_32x32x16_bf16 v[112:127], v[234:237], v[136:139], v[112:127]
	ds_read_b128 v[234:237], v204 offset:36864
	v_exp_f32_e32 v164, v164
	v_exp_f32_e32 v165, v165
	v_add_f32_e32 v163, v163, v164
	v_exp_f32_e32 v166, v166
	s_waitcnt lgkmcnt(8)
	v_mfma_f32_32x32x16_bf16 v[80:95], v[250:253], v[136:139], v[80:95]
	ds_read_b128 v[250:253], v204 offset:40960
	v_add_f32_e32 v163, v163, v165
	v_exp_f32_e32 v167, v167
	v_add_f32_e32 v163, v163, v166
	v_cvt_pk_bf16_f32 v164, v164, v165
	s_waitcnt lgkmcnt(8)
	v_mfma_f32_32x32x16_bf16 v[48:63], v[216:219], v[136:139], v[48:63]
	ds_read_b128 v[216:219], v204 offset:45056
	v_exp_f32_e32 v168, v168
	v_add_f32_e32 v163, v163, v167
	v_exp_f32_e32 v169, v169
	v_add_f32_e32 v163, v163, v168
	s_waitcnt lgkmcnt(8)
	v_mfma_f32_32x32x16_bf16 v[16:31], v[238:241], v[136:139], v[16:31]
	ds_read_b128 v[238:241], v205 offset:32768
	v_cvt_pk_bf16_f32 v165, v166, v167
	v_exp_f32_e32 v170, v170
	v_add_f32_e32 v163, v163, v169
	v_exp_f32_e32 v171, v171
	s_waitcnt lgkmcnt(8)
	v_mfma_f32_32x32x16_bf16 v[112:127], v[220:223], v[140:143], v[112:127]
	ds_read_b128 v[220:223], v205 offset:36864
	v_add_f32_e32 v163, v163, v170
	v_cvt_pk_bf16_f32 v166, v168, v169
	v_exp_f32_e32 v172, v172
	v_add_f32_e32 v163, v163, v171
	s_waitcnt lgkmcnt(8)
	v_mfma_f32_32x32x16_bf16 v[80:95], v[242:245], v[140:143], v[80:95]
	ds_read_b128 v[242:245], v205 offset:40960
	v_exp_f32_e32 v173, v173
	v_add_f32_e32 v163, v163, v172
	v_cvt_pk_bf16_f32 v167, v170, v171
	v_exp_f32_e32 v174, v174
	s_waitcnt lgkmcnt(8)
	v_mfma_f32_32x32x16_bf16 v[48:63], v[224:227], v[140:143], v[48:63]
	ds_read_b128 v[224:227], v205 offset:45056
	v_add_f32_e32 v163, v163, v173
	v_exp_f32_e32 v175, v175
	v_add_f32_e32 v163, v163, v174
	v_cvt_pk_bf16_f32 v168, v172, v173
	s_waitcnt lgkmcnt(8)
	v_mfma_f32_32x32x16_bf16 v[16:31], v[246:249], v[140:143], v[16:31]
	ds_read_b128 v[246:249], v206 offset:32768
	v_exp_f32_e32 v176, v176
	v_add_f32_e32 v163, v163, v175
	v_exp_f32_e32 v177, v177
	v_add_f32_e32 v163, v163, v176
	s_waitcnt lgkmcnt(8)
	v_mfma_f32_32x32x16_bf16 v[96:111], v[212:215], v[164:167], v[96:111]
	ds_read_b128 v[212:215], v206 offset:36864
	v_cvt_pk_bf16_f32 v169, v174, v175
	v_exp_f32_e32 v178, v178
	v_add_f32_e32 v163, v163, v177
	v_exp_f32_e32 v179, v179
	s_waitcnt lgkmcnt(8)
	v_mfma_f32_32x32x16_bf16 v[64:79], v[234:237], v[164:167], v[64:79]
	ds_read_b128 v[234:237], v206 offset:40960
	v_add_f32_e32 v163, v163, v178
	v_cvt_pk_bf16_f32 v170, v176, v177
	v_add_f32_e32 v163, v163, v179
	v_cvt_pk_bf16_f32 v171, v178, v179
	s_waitcnt lgkmcnt(8)
	v_mfma_f32_32x32x16_bf16 v[32:47], v[250:253], v[164:167], v[32:47]
	ds_read_b128 v[250:253], v206 offset:45056
	v_exp_f32_e32 v180, v180
	v_exp_f32_e32 v181, v181
	v_add_f32_e32 v163, v163, v180
	v_exp_f32_e32 v182, v182
	s_waitcnt lgkmcnt(8)
	v_mfma_f32_32x32x16_bf16 v[0:15], v[216:219], v[164:167], v[0:15]
	ds_read_b128 v[216:219], v207 offset:32768
	v_add_f32_e32 v163, v163, v181
	v_exp_f32_e32 v183, v183
	v_add_f32_e32 v163, v163, v182
	v_cvt_pk_bf16_f32 v172, v180, v181
	s_waitcnt lgkmcnt(8)
	v_mfma_f32_32x32x16_bf16 v[96:111], v[238:241], v[168:171], v[96:111]
	ds_read_b128 v[238:241], v207 offset:36864
	v_exp_f32_e32 v184, v184
	v_add_f32_e32 v163, v163, v183
	v_exp_f32_e32 v185, v185
	v_add_f32_e32 v163, v163, v184
	s_waitcnt lgkmcnt(8)
	v_mfma_f32_32x32x16_bf16 v[64:79], v[220:223], v[168:171], v[64:79]
	ds_read_b128 v[220:223], v207 offset:40960
	v_cvt_pk_bf16_f32 v173, v182, v183
	v_exp_f32_e32 v186, v186
	v_add_f32_e32 v163, v163, v185
	v_exp_f32_e32 v187, v187
	s_waitcnt lgkmcnt(8)
	v_mfma_f32_32x32x16_bf16 v[32:47], v[242:245], v[168:171], v[32:47]
	ds_read_b128 v[242:245], v207 offset:45056
	v_add_f32_e32 v163, v163, v186
	v_cvt_pk_bf16_f32 v174, v184, v185
	v_exp_f32_e32 v188, v188
	v_add_f32_e32 v163, v163, v187
	s_waitcnt lgkmcnt(8)
	v_mfma_f32_32x32x16_bf16 v[0:15], v[224:227], v[168:171], v[0:15]
	v_exp_f32_e32 v189, v189
	v_add_f32_e32 v163, v163, v188
	v_cvt_pk_bf16_f32 v175, v186, v187
	v_exp_f32_e32 v190, v190
	s_waitcnt lgkmcnt(7)
	v_mfma_f32_32x32x16_bf16 v[96:111], v[246:249], v[172:175], v[96:111]
	v_add_f32_e32 v163, v163, v189
	v_exp_f32_e32 v191, v191
	v_add_f32_e32 v163, v163, v190
	v_cvt_pk_bf16_f32 v176, v188, v189
	s_waitcnt lgkmcnt(6)
	v_mfma_f32_32x32x16_bf16 v[64:79], v[212:215], v[172:175], v[64:79]
	v_exp_f32_e32 v192, v192
	v_add_f32_e32 v163, v163, v191
	v_exp_f32_e32 v193, v193
	v_add_f32_e32 v163, v163, v192
	s_waitcnt lgkmcnt(5)
	v_mfma_f32_32x32x16_bf16 v[32:47], v[234:237], v[172:175], v[32:47]
	v_cvt_pk_bf16_f32 v177, v190, v191
	v_exp_f32_e32 v194, v194
	v_add_f32_e32 v163, v163, v193
	v_exp_f32_e32 v195, v195
	s_waitcnt lgkmcnt(4)
	v_mfma_f32_32x32x16_bf16 v[0:15], v[250:253], v[172:175], v[0:15]
	v_add_f32_e32 v163, v163, v194
	v_cvt_pk_bf16_f32 v178, v192, v193
	v_add_f32_e32 v163, v163, v195
	v_cvt_pk_bf16_f32 v179, v194, v195
	ds_read_b128 v[180:183], v228
	ds_read_b128 v[184:187], v228 offset:32
	ds_read_b128 v[188:191], v228 offset:64
	ds_read_b128 v[192:195], v228 offset:96
	s_waitcnt lgkmcnt(4)
	s_waitcnt vmcnt(0)
	s_add_i32 s44, s44, 2
	s_cmp_gt_u32 s44, s45
	s_barrier
; #define MFMA32(a, b, c) __builtin_amdgcn_mfma_f32_32x32x16_bf16((a), (b), (c), 0, 0, 0)
; __device__ __forceinline__ void attn_phase_fast(LAS unsigned char* lds, const bf16_t* q, const bf16_t* k, const bf16_t* vT, bf16_t* mixed, float lam, const int wave_s) {
;     ...
;                     o[m][db] = MFMA32(v0, p0, o[m][db]); o[m][db] = MFMA32(v1, p1, o[m][db]); o[m][db] = MFMA32(v2, p2, o[m][db]); o[m][db] = MFMA32(v3, p3, o[m][db]);
;                     if (db == 1) __builtin_amdgcn_sched_barrier(0);
;     ...
;         const float l0 = l[0] + __shfl_xor(l[0], 32), l1 = l[1] + __shfl_xor(l[1], 32);
;         const float c0 = 1.0f / l0, c1 = lam / l1;
;         float ss = 0.f;
; #pragma unroll
;         for (int db = 0; db < 4; ++db)
; #pragma unroll
;             for (int i = 0; i < 16; ++i) { const float v = o[0][db][i] * c0 - o[1][db][i] * c1; o[0][db][i] = v; ss += v * v; }
	s_cbranch_scc0 .Lattn_tile_loop
	v_mfma_f32_32x32x16_bf16 v[96:111], v[216:219], v[176:179], v[96:111]
	v_mfma_f32_32x32x16_bf16 v[64:79], v[238:241], v[176:179], v[64:79]
	v_mfma_f32_32x32x16_bf16 v[32:47], v[220:223], v[176:179], v[32:47]
	v_mfma_f32_32x32x16_bf16 v[0:15], v[242:245], v[176:179], v[0:15]
	s_mov_b32 m0, s50
	s_waitcnt lgkmcnt(0)
	v_and_b32_e32 v129, 64, v231
	v_xor_b32_e32 v128, 32, v231
	v_add_u32_e32 v129, 64, v129
	v_cmp_lt_i32_e32 vcc, v128, v129
	s_nop 1
	v_cndmask_b32_e32 v128, v231, v128, vcc
	v_lshlrev_b32_e32 v130, 2, v128
	v_mov_b32_e32 v128, v162
	v_mov_b32_e32 v129, v163
	ds_bpermute_b32 v132, v130, v128
	ds_bpermute_b32 v133, v130, v129
	s_lshl_b32 s0, s0, 1
	s_add_i32 s43, s43, s82
	s_cmpk_gt_i32 s43, 0x7ff
	s_waitcnt lgkmcnt(0)
	v_pk_add_f32 v[128:129], v[128:129], v[132:133]
	s_nop 0
	v_div_scale_f32 v131, s[2:3], v129, v129, v229
	v_rcp_f32_e32 v132, v131
	s_nop 0
	v_fma_f32 v133, -v131, v132, 1.0
	v_fmac_f32_e32 v132, v133, v132
	v_div_scale_f32 v133, vcc, v229, v129, v229
	v_mul_f32_e32 v134, v133, v132
	v_fma_f32 v135, -v131, v134, v133
	v_fmac_f32_e32 v134, v135, v132
	v_fma_f32 v131, -v131, v134, v133
	v_div_scale_f32 v133, s[2:3], v128, v128, 1.0
	v_rcp_f32_e32 v135, v133
	v_div_fmas_f32 v131, v131, v132, v134
	v_div_fixup_f32 v129, v131, v129, v229
	v_fma_f32 v131, -v133, v135, 1.0
	v_fmac_f32_e32 v135, v131, v135
	v_div_scale_f32 v131, vcc, 1.0, v128, 1.0
	v_mul_f32_e32 v132, v131, v135
	v_fma_f32 v134, -v133, v132, v131
	v_fmac_f32_e32 v132, v134, v135
	v_fma_f32 v131, -v133, v132, v131
	v_div_fmas_f32 v131, v131, v135, v132
	v_div_fixup_f32 v128, v131, v128, 1.0
	v_mov_b32_e32 v133, v96
	v_mov_b32_e32 v96, v113
	v_pk_mul_f32 v[96:97], v[96:97], v[128:129]
	v_mov_b32_e32 v132, v112
	v_sub_f32_e32 v113, v96, v97
	v_mov_b32_e32 v96, v114
	v_mov_b32_e32 v97, v98
	v_pk_mul_f32 v[96:97], v[96:97], v[128:129]
	v_mov_b32_e32 v98, v115
	v_sub_f32_e32 v114, v96, v97
	v_pk_mul_f32 v[96:97], v[98:99], v[128:129]
	v_pk_mul_f32 v[132:133], v[132:133], v[128:129]
	v_sub_f32_e32 v98, v96, v97
	v_mov_b32_e32 v96, v116
	v_mov_b32_e32 v97, v100
	v_pk_mul_f32 v[96:97], v[96:97], v[128:129]
	v_mov_b32_e32 v100, v117
	v_sub_f32_e32 v99, v96, v97
	v_pk_mul_f32 v[96:97], v[100:101], v[128:129]
	v_sub_f32_e32 v112, v132, v133
	v_sub_f32_e32 v100, v96, v97
	v_mov_b32_e32 v96, v118
	v_mov_b32_e32 v97, v102
	v_pk_mul_f32 v[96:97], v[96:97], v[128:129]
	v_mov_b32_e32 v102, v119
	v_sub_f32_e32 v101, v96, v97
	v_pk_mul_f32 v[96:97], v[102:103], v[128:129]
	s_nop 0
	v_sub_f32_e32 v102, v96, v97
	v_mov_b32_e32 v96, v120
	v_mov_b32_e32 v97, v104
	v_pk_mul_f32 v[96:97], v[96:97], v[128:129]
	v_mov_b32_e32 v104, v121
	v_sub_f32_e32 v103, v96, v97
	v_pk_mul_f32 v[96:97], v[104:105], v[128:129]
	s_nop 0
	v_sub_f32_e32 v104, v96, v97
	v_mov_b32_e32 v96, v122
	v_mov_b32_e32 v97, v106
	v_pk_mul_f32 v[96:97], v[96:97], v[128:129]
	v_mov_b32_e32 v106, v123
	v_sub_f32_e32 v105, v96, v97
	v_pk_mul_f32 v[96:97], v[106:107], v[128:129]
	s_nop 0
	v_sub_f32_e32 v106, v96, v97
	v_mov_b32_e32 v96, v124
	v_mov_b32_e32 v97, v108
	v_pk_mul_f32 v[96:97], v[96:97], v[128:129]
	v_mov_b32_e32 v108, v125
	v_sub_f32_e32 v107, v96, v97
	v_pk_mul_f32 v[96:97], v[108:109], v[128:129]
	s_nop 0
	v_sub_f32_e32 v108, v96, v97
	v_mov_b32_e32 v96, v126
	v_mov_b32_e32 v97, v110
	v_pk_mul_f32 v[96:97], v[96:97], v[128:129]
	v_mov_b32_e32 v110, v127
	v_sub_f32_e32 v109, v96, v97
	v_pk_mul_f32 v[96:97], v[110:111], v[128:129]
	s_nop 0
	v_sub_f32_e32 v110, v96, v97
	v_mov_b32_e32 v97, v64
	v_mov_b32_e32 v64, v81
	v_pk_mul_f32 v[64:65], v[64:65], v[128:129]
	v_mov_b32_e32 v96, v80
	v_sub_f32_e32 v81, v64, v65
	v_mov_b32_e32 v64, v82
	v_mov_b32_e32 v65, v66
	v_pk_mul_f32 v[64:65], v[64:65], v[128:129]
	v_mov_b32_e32 v66, v83
	v_sub_f32_e32 v82, v64, v65
	v_pk_mul_f32 v[64:65], v[66:67], v[128:129]
	v_pk_mul_f32 v[96:97], v[96:97], v[128:129]
	v_sub_f32_e32 v66, v64, v65
	v_mov_b32_e32 v64, v84
	v_mov_b32_e32 v65, v68
	v_pk_mul_f32 v[64:65], v[64:65], v[128:129]
	v_mov_b32_e32 v68, v85
	v_sub_f32_e32 v67, v64, v65
	v_pk_mul_f32 v[64:65], v[68:69], v[128:129]
	v_sub_f32_e32 v80, v96, v97
	v_sub_f32_e32 v68, v64, v65
	v_mov_b32_e32 v64, v86
	v_mov_b32_e32 v65, v70
	v_pk_mul_f32 v[64:65], v[64:65], v[128:129]
	v_mov_b32_e32 v70, v87
	v_sub_f32_e32 v69, v64, v65
	v_pk_mul_f32 v[64:65], v[70:71], v[128:129]
	s_nop 0
	v_sub_f32_e32 v70, v64, v65
	v_mov_b32_e32 v64, v88
	v_mov_b32_e32 v65, v72
	v_pk_mul_f32 v[64:65], v[64:65], v[128:129]
	v_mov_b32_e32 v72, v89
	v_sub_f32_e32 v71, v64, v65
	v_pk_mul_f32 v[64:65], v[72:73], v[128:129]
	s_nop 0
	v_sub_f32_e32 v72, v64, v65
	v_mov_b32_e32 v64, v90
	v_mov_b32_e32 v65, v74
	v_pk_mul_f32 v[64:65], v[64:65], v[128:129]
	v_mov_b32_e32 v74, v91
	v_sub_f32_e32 v73, v64, v65
	v_pk_mul_f32 v[64:65], v[74:75], v[128:129]
	s_nop 0
	v_sub_f32_e32 v74, v64, v65
	v_mov_b32_e32 v64, v92
	v_mov_b32_e32 v65, v76
	v_pk_mul_f32 v[64:65], v[64:65], v[128:129]
	v_mov_b32_e32 v76, v93
	v_sub_f32_e32 v75, v64, v65
	v_pk_mul_f32 v[64:65], v[76:77], v[128:129]
	s_nop 0
	v_sub_f32_e32 v76, v64, v65
	v_mov_b32_e32 v64, v94
	v_mov_b32_e32 v65, v78
	v_pk_mul_f32 v[64:65], v[64:65], v[128:129]
	v_mov_b32_e32 v78, v95
	v_sub_f32_e32 v77, v64, v65
	v_pk_mul_f32 v[64:65], v[78:79], v[128:129]
	s_nop 0
	v_sub_f32_e32 v78, v64, v65
	v_mov_b32_e32 v65, v32
	v_mov_b32_e32 v32, v49
	v_pk_mul_f32 v[32:33], v[32:33], v[128:129]
	v_mov_b32_e32 v64, v48
	v_sub_f32_e32 v49, v32, v33
	v_mov_b32_e32 v32, v50
	v_mov_b32_e32 v33, v34
	v_pk_mul_f32 v[32:33], v[32:33], v[128:129]
	v_mov_b32_e32 v34, v51
	v_sub_f32_e32 v50, v32, v33
	v_pk_mul_f32 v[32:33], v[34:35], v[128:129]
; __device__ __forceinline__ void attn_phase_fast(LAS unsigned char* lds, const bf16_t* q, const bf16_t* k, const bf16_t* vT, bf16_t* mixed, float lam, const int wave_s) {
;     ...
;         float ss = 0.f;
; #pragma unroll
;         for (int db = 0; db < 4; ++db)
; #pragma unroll
;             for (int i = 0; i < 16; ++i) { const float v = o[0][db][i] * c0 - o[1][db][i] * c1; o[0][db][i] = v; ss += v * v; }
;         ss += __shfl_xor(ss, 32);
;         const float rstd = rsqrtf(ss * (1.0f / 128.0f) + EPSV);
	v_pk_mul_f32 v[64:65], v[64:65], v[128:129]
	v_sub_f32_e32 v34, v32, v33
	v_mov_b32_e32 v32, v52
	v_mov_b32_e32 v33, v36
	v_pk_mul_f32 v[32:33], v[32:33], v[128:129]
	v_mov_b32_e32 v36, v53
	v_sub_f32_e32 v35, v32, v33
	v_pk_mul_f32 v[32:33], v[36:37], v[128:129]
	v_sub_f32_e32 v48, v64, v65
	v_sub_f32_e32 v36, v32, v33
	v_mov_b32_e32 v32, v54
	v_mov_b32_e32 v33, v38
	v_pk_mul_f32 v[32:33], v[32:33], v[128:129]
	v_mov_b32_e32 v38, v55
	v_sub_f32_e32 v37, v32, v33
	v_pk_mul_f32 v[32:33], v[38:39], v[128:129]
	s_nop 0
	v_sub_f32_e32 v38, v32, v33
	v_mov_b32_e32 v32, v56
	v_mov_b32_e32 v33, v40
	v_pk_mul_f32 v[32:33], v[32:33], v[128:129]
	v_mov_b32_e32 v40, v57
	v_sub_f32_e32 v39, v32, v33
	v_pk_mul_f32 v[32:33], v[40:41], v[128:129]
	s_nop 0
	v_sub_f32_e32 v40, v32, v33
	v_mov_b32_e32 v32, v58
	v_mov_b32_e32 v33, v42
	v_pk_mul_f32 v[32:33], v[32:33], v[128:129]
	v_mov_b32_e32 v42, v59
	v_sub_f32_e32 v41, v32, v33
	v_pk_mul_f32 v[32:33], v[42:43], v[128:129]
	s_nop 0
	v_sub_f32_e32 v42, v32, v33
	v_mov_b32_e32 v32, v60
	v_mov_b32_e32 v33, v44
	v_pk_mul_f32 v[32:33], v[32:33], v[128:129]
	v_mov_b32_e32 v44, v61
	v_sub_f32_e32 v43, v32, v33
	v_pk_mul_f32 v[32:33], v[44:45], v[128:129]
	s_nop 0
	v_sub_f32_e32 v44, v32, v33
	v_mov_b32_e32 v32, v62
	v_mov_b32_e32 v33, v46
	v_pk_mul_f32 v[32:33], v[32:33], v[128:129]
	v_mov_b32_e32 v46, v63
	v_sub_f32_e32 v45, v32, v33
	v_pk_mul_f32 v[32:33], v[46:47], v[128:129]
	s_nop 0
	v_sub_f32_e32 v46, v32, v33
	v_mov_b32_e32 v32, v16
	v_mov_b32_e32 v33, v0
	v_mov_b32_e32 v0, v17
	v_pk_mul_f32 v[32:33], v[32:33], v[128:129]
	v_pk_mul_f32 v[0:1], v[0:1], v[128:129]
	v_sub_f32_e32 v32, v32, v33
	v_sub_f32_e32 v33, v0, v1
	v_mov_b32_e32 v0, v18
	v_mov_b32_e32 v1, v2
	v_pk_mul_f32 v[0:1], v[0:1], v[128:129]
	v_mov_b32_e32 v2, v19
	v_sub_f32_e32 v47, v0, v1
	v_pk_mul_f32 v[0:1], v[2:3], v[128:129]
	s_nop 0
	v_sub_f32_e32 v51, v0, v1
	v_mov_b32_e32 v0, v20
	v_mov_b32_e32 v1, v4
	v_pk_mul_f32 v[0:1], v[0:1], v[128:129]
	v_mov_b32_e32 v4, v21
	v_sub_f32_e32 v20, v0, v1
	v_pk_mul_f32 v[0:1], v[4:5], v[128:129]
	s_nop 0
	v_sub_f32_e32 v21, v0, v1
	v_mov_b32_e32 v0, v22
	v_mul_f32_e32 v22, v112, v112
	v_fmac_f32_e32 v22, v113, v113
	v_fmac_f32_e32 v22, v114, v114
	v_fmac_f32_e32 v22, v98, v98
	v_fmac_f32_e32 v22, v99, v99
	v_fmac_f32_e32 v22, v100, v100
	v_fmac_f32_e32 v22, v101, v101
	v_fmac_f32_e32 v22, v102, v102
	v_fmac_f32_e32 v22, v103, v103
	v_fmac_f32_e32 v22, v104, v104
	v_fmac_f32_e32 v22, v105, v105
	v_fmac_f32_e32 v22, v106, v106
	v_fmac_f32_e32 v22, v107, v107
	v_fmac_f32_e32 v22, v108, v108
	v_fmac_f32_e32 v22, v109, v109
	v_fmac_f32_e32 v22, v110, v110
	v_fmac_f32_e32 v22, v80, v80
	v_fmac_f32_e32 v22, v81, v81
	v_fmac_f32_e32 v22, v82, v82
	v_fmac_f32_e32 v22, v66, v66
	v_fmac_f32_e32 v22, v67, v67
	v_fmac_f32_e32 v22, v68, v68
	v_fmac_f32_e32 v22, v69, v69
	v_fmac_f32_e32 v22, v70, v70
	v_fmac_f32_e32 v22, v71, v71
	v_fmac_f32_e32 v22, v72, v72
	v_fmac_f32_e32 v22, v73, v73
	v_fmac_f32_e32 v22, v74, v74
	v_fmac_f32_e32 v22, v75, v75
	v_fmac_f32_e32 v22, v76, v76
	v_fmac_f32_e32 v22, v77, v77
	v_fmac_f32_e32 v22, v78, v78
	v_fmac_f32_e32 v22, v48, v48
	v_fmac_f32_e32 v22, v49, v49
	v_fmac_f32_e32 v22, v50, v50
	v_fmac_f32_e32 v22, v34, v34
	v_fmac_f32_e32 v22, v35, v35
	v_fmac_f32_e32 v22, v36, v36
	v_fmac_f32_e32 v22, v37, v37
	v_fmac_f32_e32 v22, v38, v38
	v_fmac_f32_e32 v22, v39, v39
	v_fmac_f32_e32 v22, v40, v40
	v_fmac_f32_e32 v22, v41, v41
	v_fmac_f32_e32 v22, v42, v42
	v_fmac_f32_e32 v22, v43, v43
	v_fmac_f32_e32 v22, v44, v44
	v_fmac_f32_e32 v22, v45, v45
	v_fmac_f32_e32 v22, v46, v46
	v_fmac_f32_e32 v22, v32, v32
	v_mov_b32_e32 v1, v6
	v_mov_b32_e32 v6, v23
	v_fmac_f32_e32 v22, v33, v33
	v_pk_mul_f32 v[0:1], v[0:1], v[128:129]
	v_pk_mul_f32 v[2:3], v[6:7], v[128:129]
	v_fmac_f32_e32 v22, v47, v47
	v_mov_b32_e32 v4, v2
	v_mov_b32_e32 v5, v0
	v_mov_b32_e32 v0, v3
	v_mov_b32_e32 v2, v24
	v_mov_b32_e32 v3, v8
	v_mov_b32_e32 v8, v25
	v_fmac_f32_e32 v22, v51, v51
	v_pk_add_f32 v[0:1], v[4:5], v[0:1] neg_lo:[0,1] neg_hi:[0,1]
	v_pk_mul_f32 v[2:3], v[2:3], v[128:129]
	v_pk_mul_f32 v[4:5], v[8:9], v[128:129]
	v_fmac_f32_e32 v22, v20, v20
	v_pk_mul_f32 v[16:17], v[0:1], v[0:1]
	v_mov_b32_e32 v6, v4
	v_mov_b32_e32 v7, v2
	v_mov_b32_e32 v2, v5
	v_mov_b32_e32 v4, v26
	v_mov_b32_e32 v5, v10
	v_mov_b32_e32 v10, v27
	v_fmac_f32_e32 v22, v21, v21
	v_pk_add_f32 v[2:3], v[6:7], v[2:3] neg_lo:[0,1] neg_hi:[0,1]
	v_pk_mul_f32 v[4:5], v[4:5], v[128:129]
	v_pk_mul_f32 v[6:7], v[10:11], v[128:129]
	v_add_f32_e32 v17, v17, v22
	v_pk_mul_f32 v[18:19], v[2:3], v[2:3]
	v_mov_b32_e32 v8, v6
	v_mov_b32_e32 v9, v4
	v_mov_b32_e32 v4, v7
	v_add_f32_e32 v16, v16, v17
	v_pk_add_f32 v[4:5], v[8:9], v[4:5] neg_lo:[0,1] neg_hi:[0,1]
	v_mov_b32_e32 v8, v129
	v_add_f32_e32 v16, v19, v16
	v_pk_mul_f32 v[10:11], v[4:5], v[4:5]
	v_pk_mul_f32 v[6:7], v[12:13], v[8:9] op_sel_hi:[1,0]
	v_add_f32_e32 v16, v18, v16
	v_pk_fma_f32 v[6:7], v[28:29], v[128:129], v[6:7] op_sel_hi:[1,0,1] neg_lo:[0,0,1] neg_hi:[0,0,1]
	v_add_f32_e32 v11, v11, v16
	v_pk_mul_f32 v[12:13], v[6:7], v[6:7]
	v_pk_mul_f32 v[8:9], v[14:15], v[8:9] op_sel_hi:[1,0]
	v_add_f32_e32 v10, v10, v11
	v_pk_fma_f32 v[8:9], v[30:31], v[128:129], v[8:9] op_sel_hi:[1,0,1] neg_lo:[0,0,1] neg_hi:[0,0,1]
	v_add_f32_e32 v10, v12, v10
	v_pk_mul_f32 v[14:15], v[8:9], v[8:9]
	v_add_f32_e32 v10, v13, v10
	v_add_f32_e32 v10, v14, v10
	v_add_f32_e32 v10, v15, v10
	ds_bpermute_b32 v11, v130, v10
	v_mbcnt_lo_u32_b32 v12, -1, 0
	v_mbcnt_hi_u32_b32 v12, -1, v12
	s_waitcnt lgkmcnt(0)
; __device__ __forceinline__ unsigned cvt_pk_bf16(float lo, float hi) { unsigned r; asm volatile("v_cvt_pk_bf16_f32 %0, %1, %2" : "=v"(r) : "v"(lo), "v"(hi)); return r; }
; __device__ __forceinline__ int lane_id() { int l; asm volatile("v_mbcnt_lo_u32_b32 %0, -1, 0\n\tv_mbcnt_hi_u32_b32 %0, -1, %0" : "=v"(l)); return l; }
; __device__ __forceinline__ void attn_phase_fast(LAS unsigned char* lds, const bf16_t* q, const bf16_t* k, const bf16_t* vT, bf16_t* mixed, float lam, const int wave_s) {
;     ...
;         ss += __shfl_xor(ss, 32);
;         const float rstd = rsqrtf(ss * (1.0f / 128.0f) + EPSV);
;         int lane2 = lane_id(); asm volatile("" : "+v"(lane2));
;         bf16_t* orow = mixed + ((size_t)tok0 + qb * 256 + wid * 32 + (lane2 & 31)) * DM + h * 128 + 4 * (lane2 >> 5);
; #pragma unroll
;         for (int db = 0; db < 4; ++db)
; #pragma unroll
;             for (int i4 = 0; i4 < 4; ++i4) {
;                 u32x2 w; w.x = cvt_pk_bf16(o[0][db][4 * i4] * rstd, o[0][db][4 * i4 + 1] * rstd); w.y = cvt_pk_bf16(o[0][db][4 * i4 + 2] * rstd, o[0][db][4 * i4 + 3] * rstd);
;                 *(u32x2*)(orow + 32 * db + 8 * i4) = w;
;             }
	v_add_f32_e32 v10, v10, v11
	v_fmamk_f32 v10, v10, 0x3c000000, v232
	v_mul_f32_e32 v11, 0x4b800000, v10
	v_cmp_gt_f32_e32 vcc, s42, v10
	s_nop 0
	v_and_b32_e32 v160, 31, v12
	v_cndmask_b32_e32 v10, v10, v11, vcc
	v_rsq_f32_e32 v10, v10
	v_ashrrev_i32_e32 v12, 3, v12
	v_and_b32_e32 v12, -4, v12
	v_ashrrev_i32_e32 v13, 31, v12
	v_mul_f32_e32 v11, 0x45800000, v10
	v_cndmask_b32_e32 v14, v10, v11, vcc
	v_lshl_add_u64 v[10:11], s[4:5], 0, v[160:161]
	v_lshlrev_b64 v[10:11], 11, v[10:11]
	v_lshl_add_u64 v[10:11], s[20:21], 0, v[10:11]
	v_lshl_add_u64 v[10:11], v[10:11], 0, s[0:1]
	v_lshl_add_u64 v[10:11], v[12:13], 1, v[10:11]
	v_mul_f32_e32 v12, v112, v14
	v_mul_f32_e32 v13, v113, v14
	v_cvt_pk_bf16_f32 v12, v12, v13
	v_mul_f32_e32 v13, v114, v14
	v_mul_f32_e32 v15, v98, v14
	v_cvt_pk_bf16_f32 v13, v13, v15
	global_store_dwordx2 v[10:11], v[12:13], off
	v_mul_f32_e32 v12, v99, v14
	v_mul_f32_e32 v13, v100, v14
	v_cvt_pk_bf16_f32 v12, v12, v13
	v_mul_f32_e32 v13, v101, v14
	v_mul_f32_e32 v15, v102, v14
	v_cvt_pk_bf16_f32 v13, v13, v15
	global_store_dwordx2 v[10:11], v[12:13], off offset:16
	v_mul_f32_e32 v12, v103, v14
	v_mul_f32_e32 v13, v104, v14
	v_cvt_pk_bf16_f32 v12, v12, v13
	v_mul_f32_e32 v13, v105, v14
	v_mul_f32_e32 v15, v106, v14
	v_cvt_pk_bf16_f32 v13, v13, v15
	global_store_dwordx2 v[10:11], v[12:13], off offset:32
	v_mul_f32_e32 v12, v107, v14
	v_mul_f32_e32 v13, v108, v14
	v_cvt_pk_bf16_f32 v12, v12, v13
	v_mul_f32_e32 v13, v109, v14
	v_mul_f32_e32 v15, v110, v14
	v_cvt_pk_bf16_f32 v13, v13, v15
	global_store_dwordx2 v[10:11], v[12:13], off offset:48
	v_mul_f32_e32 v12, v80, v14
	v_mul_f32_e32 v13, v81, v14
	v_cvt_pk_bf16_f32 v12, v12, v13
	v_mul_f32_e32 v13, v82, v14
	v_mul_f32_e32 v15, v66, v14
	v_cvt_pk_bf16_f32 v13, v13, v15
	global_store_dwordx2 v[10:11], v[12:13], off offset:64
	v_mul_f32_e32 v12, v67, v14
	v_mul_f32_e32 v13, v68, v14
	v_cvt_pk_bf16_f32 v12, v12, v13
	v_mul_f32_e32 v13, v69, v14
	v_mul_f32_e32 v15, v70, v14
	v_cvt_pk_bf16_f32 v13, v13, v15
	global_store_dwordx2 v[10:11], v[12:13], off offset:80
	v_mul_f32_e32 v12, v71, v14
	v_mul_f32_e32 v13, v72, v14
	v_cvt_pk_bf16_f32 v12, v12, v13
	v_mul_f32_e32 v13, v73, v14
	v_mul_f32_e32 v15, v74, v14
	v_cvt_pk_bf16_f32 v13, v13, v15
	global_store_dwordx2 v[10:11], v[12:13], off offset:96
	v_mul_f32_e32 v12, v75, v14
	v_mul_f32_e32 v13, v76, v14
	v_cvt_pk_bf16_f32 v12, v12, v13
	v_mul_f32_e32 v13, v77, v14
	v_mul_f32_e32 v15, v78, v14
	v_cvt_pk_bf16_f32 v13, v13, v15
	global_store_dwordx2 v[10:11], v[12:13], off offset:112
	v_mul_f32_e32 v12, v48, v14
	v_mul_f32_e32 v13, v49, v14
	v_cvt_pk_bf16_f32 v12, v12, v13
	v_mul_f32_e32 v13, v50, v14
	v_mul_f32_e32 v15, v34, v14
	v_cvt_pk_bf16_f32 v13, v13, v15
	global_store_dwordx2 v[10:11], v[12:13], off offset:128
	v_mul_f32_e32 v12, v35, v14
	v_mul_f32_e32 v13, v36, v14
	v_cvt_pk_bf16_f32 v12, v12, v13
	v_mul_f32_e32 v13, v37, v14
	v_mul_f32_e32 v15, v38, v14
	v_cvt_pk_bf16_f32 v13, v13, v15
	global_store_dwordx2 v[10:11], v[12:13], off offset:144
	v_mul_f32_e32 v12, v39, v14
	v_mul_f32_e32 v13, v40, v14
	v_cvt_pk_bf16_f32 v12, v12, v13
	v_mul_f32_e32 v13, v41, v14
	v_mul_f32_e32 v15, v42, v14
	v_cvt_pk_bf16_f32 v13, v13, v15
	global_store_dwordx2 v[10:11], v[12:13], off offset:160
	v_mul_f32_e32 v12, v43, v14
	v_mul_f32_e32 v13, v44, v14
	v_cvt_pk_bf16_f32 v12, v12, v13
	v_mul_f32_e32 v13, v45, v14
	v_mul_f32_e32 v15, v46, v14
	v_cvt_pk_bf16_f32 v13, v13, v15
	global_store_dwordx2 v[10:11], v[12:13], off offset:176
	v_mul_f32_e32 v12, v32, v14
	v_mul_f32_e32 v13, v33, v14
	v_cvt_pk_bf16_f32 v12, v12, v13
	v_mul_f32_e32 v13, v47, v14
	v_mul_f32_e32 v15, v51, v14
	v_cvt_pk_bf16_f32 v13, v13, v15
	global_store_dwordx2 v[10:11], v[12:13], off offset:192
	v_mul_f32_e32 v12, v20, v14
	v_mul_f32_e32 v13, v21, v14
	v_mul_f32_e32 v1, v1, v14
	v_mul_f32_e32 v0, v0, v14
	v_cvt_pk_bf16_f32 v12, v12, v13
	v_cvt_pk_bf16_f32 v13, v1, v0
	v_mul_f32_e32 v0, v3, v14
	v_mul_f32_e32 v1, v2, v14
	global_store_dwordx2 v[10:11], v[12:13], off offset:208
	v_cvt_pk_bf16_f32 v0, v0, v1
	v_mul_f32_e32 v1, v5, v14
	v_mul_f32_e32 v2, v4, v14
	v_cvt_pk_bf16_f32 v1, v1, v2
	global_store_dwordx2 v[10:11], v[0:1], off offset:224
	v_mul_f32_e32 v0, v6, v14
	v_mul_f32_e32 v1, v7, v14
	v_cvt_pk_bf16_f32 v0, v0, v1
	v_mul_f32_e32 v1, v8, v14
	v_mul_f32_e32 v2, v9, v14
	v_cvt_pk_bf16_f32 v1, v1, v2
	global_store_dwordx2 v[10:11], v[0:1], off offset:240
	s_cbranch_scc0 .LBB0_390

; #define LAS __attribute__((address_space(3)))
;     template <bool BND> __device__ __forceinline__ void conv_gate(f32x4 (&acc)[2][2][4][2], const Unit& u, int wr, int wc, int fr, int fq, int tok0, int pcol) const {
;         const int fcol = u.pn * 128 + pcol;
; #pragma unroll
;         for (int n = 0; n < 2; ++n) {
;             f32x4 w0[2], w1[2], w2[2], bb[2];
; #pragma unroll
;             for (int bj = 0; bj < 2; ++bj) { const int c = bj * DFF + fcol + 4 * n;
;                 w0[bj] = *(const f32x4*)(convw + c); w1[bj] = *(const f32x4*)(convw + 2 * DFF + c); w2[bj] = *(const f32x4*)(convw + 4 * DFF + c); bb[bj] = *(const f32x4*)(convb + c); }
; #pragma unroll
;             for (int ai = 0; ai < 2; ++ai) {
;                 const int blk = 2 * ai + wr;
;                 f32x4 pe[2], ne[2];
; #pragma unroll
;                 for (int bj = 0; bj < 2; ++bj) {
;                     pe[bj] = blk > 0 ? *(const LAS f32x4*)(edge + ((blk - 1) * 2 + 1) * 256 + 128 * bj + pcol + 4 * n) : (f32x4){0.f, 0.f, 0.f, 0.f};
;                     ne[bj] = blk < 3 ? *(const LAS f32x4*)(edge + ((blk + 1) * 2 + 0) * 256 + 128 * bj + pcol + 4 * n) : (f32x4){0.f, 0.f, 0.f, 0.f};
;                 }
; #pragma unroll
;                 for (int m = 0; m < 4; ++m) {
;                     const int r = ai * 128 + wr * 64 + m * 16 + fr, tok = tok0 + r;
;                     bool isfirst = false, islast = false;
;                     if (BND) { const int S1 = (tok < NPROMPT ? SEQP : SEQS) - 1, pos = tok & S1; isfirst = pos == 0; islast = pos == S1; }
;                     f32x4 cv[2];
; #pragma unroll
;                     for (int bj = 0; bj < 2; ++bj) {
;                         const f32x4 cur = acc[ai][bj][m][n];
;                         const f32x4 ups = m > 0 ? acc[ai][bj][m > 0 ? m - 1 : 0][n] : pe[bj];
;                         const f32x4 dns = m < 3 ? acc[ai][bj][m < 3 ? m + 1 : 3][n] : ne[bj];
;                         f32x4 prev, next;
; #pragma unroll
;                         for (int j = 0; j < 4; ++j) {
;                             const float t1 = fr == 15 ? ups[j] : cur[j]; float pv = dpp_ror1(t1);
;                             const float t2 = fr == 0 ? dns[j] : cur[j]; float nx = dpp_ror15(t2);
;                             if (BND) { prev[j] = isfirst ? 0.f : pv; next[j] = islast ? 0.f : nx; } else { prev[j] = pv; next[j] = nx; }
;                         }
.LBB0_629:
	s_or_b64 exec, exec, s[0:1]
	v_lshl_add_u32 v190, s10, 7, v80
	v_readlane_b32 s4, v255, 0
	v_readlane_b32 s8, v255, 4
	v_readlane_b32 s9, v255, 5
	v_add_u32_e32 v80, 0xb00, v190
	v_ashrrev_i32_e32 v191, 31, v190
	v_readlane_b32 s0, v255, 31
	v_readlane_b32 s8, v255, 33
	v_ashrrev_i32_e32 v81, 31, v80
	v_lshlrev_b64 v[64:65], 2, v[190:191]
	v_readlane_b32 s5, v255, 1
	v_readlane_b32 s6, v255, 2
	v_readlane_b32 s7, v255, 3
	v_readlane_b32 s1, v255, 32
	v_readlane_b32 s9, v255, 34
	v_lshlrev_b64 v[80:81], 2, v[80:81]
	s_waitcnt lgkmcnt(0)
	s_barrier
	v_lshl_add_u64 v[224:225], s[4:5], 0, v[64:65]
	v_lshl_add_u64 v[66:67], s[0:1], 0, v[64:65]
	v_lshl_add_u64 v[68:69], s[8:9], 0, v[64:65]
	v_lshl_add_u64 v[226:227], s[6:7], 0, v[64:65]
	v_lshl_add_u64 v[82:83], s[4:5], 0, v[80:81]
	global_load_dwordx4 v[72:75], v[224:225], off
	global_load_dwordx4 v[76:79], v[66:67], off
	s_nop 0
	global_load_dwordx4 v[68:71], v[68:69], off
	v_lshl_add_u64 v[84:85], s[0:1], 0, v[80:81]
	global_load_dwordx4 v[64:67], v[226:227], off
	global_load_dwordx4 v[92:95], v[82:83], off
	global_load_dwordx4 v[88:91], v[84:85], off
	v_lshl_add_u64 v[82:83], s[8:9], 0, v[80:81]
	v_lshl_add_u64 v[80:81], s[6:7], 0, v[80:81]
	global_load_dwordx4 v[84:87], v[82:83], off
	v_readlane_b32 s4, v255, 25
	global_load_dwordx4 v[80:83], v[80:81], off
	v_readlane_b32 s0, v255, 35
	v_readlane_b32 s5, v255, 26
	v_readlane_b32 s10, v255, 6
	v_readlane_b32 s11, v255, 7
	v_add_u32_e32 v247, s0, v96
	v_cndmask_b32_e64 v96, 0, 1, s[4:5]
	v_cmp_eq_u32_e64 s[8:9], 15, v228
	v_cmp_eq_u32_e64 s[6:7], 0, v228
	s_mov_b64 s[0:1], -1
	s_and_b64 vcc, exec, s[12:13]
	v_cmp_ne_u32_e64 s[10:11], 1, v96
	s_cbranch_vccz .LBB0_695
	s_and_b64 s[14:15], s[6:7], s[80:81]
	s_andn2_b64 s[16:17], s[8:9], s[80:81]
	s_mov_b32 s20, 0x16000
	s_mov_b32 s21, 0
	s_mov_b32 s22, 0x6e000
	s_mov_b32 s23, 0
	s_mov_b32 s24, 0xfff0e000
	s_mov_b32 s25, -1
	v_mov_b64_e32 v[140:141], s[88:89]
	s_movk_i32 s4, 0x1600
	v_mad_i64_i32 v[140:141], s[12:13], v152, s4, v[140:141]
	v_lshl_add_u64 v[140:141], v[190:191], 1, v[140:141]
	ds_read_b128 v[132:135], v247
	ds_read_b128 v[136:139], v247 offset:512
	s_waitcnt vmcnt(0)
	s_waitcnt lgkmcnt(0)
	s_cmp_eq_u64 s[80:81], 0
	s_cbranch_scc1 .Lconv_keep_1
	v_mov_b32_e32 v132, 0
	v_mov_b32_e32 v133, 0
	v_mov_b32_e32 v134, 0
	v_mov_b32_e32 v135, 0
	v_mov_b32_e32 v136, 0
	v_mov_b32_e32 v137, 0
	v_mov_b32_e32 v138, 0
	v_mov_b32_e32 v139, 0
.Lconv_keep_1:
	v_cndmask_b32_e64 v100, v32, v132, s[8:9]
	v_cndmask_b32_e64 v101, v33, v133, s[8:9]
	v_cndmask_b32_e64 v102, v34, v134, s[8:9]
	v_cndmask_b32_e64 v103, v35, v135, s[8:9]
	v_cndmask_b32_e64 v104, v36, v136, s[8:9]
	v_cndmask_b32_e64 v105, v37, v137, s[8:9]
	v_cndmask_b32_e64 v106, v38, v138, s[8:9]
	v_cndmask_b32_e64 v107, v39, v139, s[8:9]
	v_cndmask_b32_e64 v108, v32, v194, s[6:7]
	v_cndmask_b32_e64 v109, v33, v195, s[6:7]
	v_cndmask_b32_e64 v110, v34, v192, s[6:7]
	v_cndmask_b32_e64 v111, v35, v193, s[6:7]
	v_cndmask_b32_e64 v112, v36, v198, s[6:7]
	v_cndmask_b32_e64 v113, v37, v199, s[6:7]
	v_cndmask_b32_e64 v114, v38, v196, s[6:7]
	v_cndmask_b32_e64 v115, v39, v197, s[6:7]
	v_fma_f32 v116, v76, v32, v64
	v_fma_f32 v117, v77, v33, v65
	v_fma_f32 v118, v78, v34, v66
	v_fma_f32 v119, v79, v35, v67
	v_fma_f32 v120, v88, v36, v80
	v_fma_f32 v121, v89, v37, v81
	v_fma_f32 v122, v90, v38, v82
	v_fma_f32 v123, v91, v39, v83
	v_fmac_f32_dpp v116, v100, v72 row_ror:1 row_mask:0xf bank_mask:0xf
	v_fmac_f32_dpp v117, v101, v73 row_ror:1 row_mask:0xf bank_mask:0xf
	v_fmac_f32_dpp v118, v102, v74 row_ror:1 row_mask:0xf bank_mask:0xf
	v_fmac_f32_dpp v119, v103, v75 row_ror:1 row_mask:0xf bank_mask:0xf
	v_fmac_f32_dpp v120, v104, v92 row_ror:1 row_mask:0xf bank_mask:0xf
	v_fmac_f32_dpp v121, v105, v93 row_ror:1 row_mask:0xf bank_mask:0xf
	v_fmac_f32_dpp v122, v106, v94 row_ror:1 row_mask:0xf bank_mask:0xf
	v_fmac_f32_dpp v123, v107, v95 row_ror:1 row_mask:0xf bank_mask:0xf
	v_fmac_f32_dpp v116, v108, v68 row_ror:15 row_mask:0xf bank_mask:0xf
	v_fmac_f32_dpp v117, v109, v69 row_ror:15 row_mask:0xf bank_mask:0xf
	v_fmac_f32_dpp v118, v110, v70 row_ror:15 row_mask:0xf bank_mask:0xf
	v_fmac_f32_dpp v119, v111, v71 row_ror:15 row_mask:0xf bank_mask:0xf
	v_fmac_f32_dpp v120, v112, v84 row_ror:15 row_mask:0xf bank_mask:0xf
	v_fmac_f32_dpp v121, v113, v85 row_ror:15 row_mask:0xf bank_mask:0xf
	v_fmac_f32_dpp v122, v114, v86 row_ror:15 row_mask:0xf bank_mask:0xf
	v_fmac_f32_dpp v123, v115, v87 row_ror:15 row_mask:0xf bank_mask:0xf
	v_mul_f32_e32 v124, 0xbfb8aa3b, v116
	v_mul_f32_e32 v125, 0xbfb8aa3b, v117
	v_mul_f32_e32 v126, 0xbfb8aa3b, v118
	v_mul_f32_e32 v127, 0xbfb8aa3b, v119
	v_exp_f32_e32 v124, v124
	v_exp_f32_e32 v125, v125
	v_exp_f32_e32 v126, v126
	v_exp_f32_e32 v127, v127
	v_add_f32_e32 v124, 1.0, v124
	v_add_f32_e32 v125, 1.0, v125
	v_add_f32_e32 v126, 1.0, v126
	v_add_f32_e32 v127, 1.0, v127
	v_rcp_f32_e32 v124, v124
	v_rcp_f32_e32 v125, v125
	v_rcp_f32_e32 v126, v126
	v_rcp_f32_e32 v127, v127
	v_mul_f32_e32 v116, v116, v124
	v_mul_f32_e32 v117, v117, v125
	v_mul_f32_e32 v118, v118, v126
	v_mul_f32_e32 v119, v119, v127
	v_mul_f32_e32 v116, v116, v120
	v_mul_f32_e32 v117, v117, v121
	v_mul_f32_e32 v118, v118, v122
	v_mul_f32_e32 v119, v119, v123
	v_cvt_pk_bf16_f32 v128, v116, v117
	v_cvt_pk_bf16_f32 v129, v118, v119
	s_mov_b64 s[18:19], exec
	s_andn2_b64 exec, exec, s[14:15]
	global_store_dwordx2 v[140:141], v[128:129], off
	s_mov_b64 exec, s[18:19]
	v_lshl_add_u64 v[140:141], v[140:141], 0, s[20:21]
	ds_read_b128 v[132:135], v246 offset:2048
	ds_read_b128 v[136:139], v246 offset:2560
	v_cndmask_b32_e64 v100, v194, v32, s[8:9]
; __device__ __forceinline__ u32x2 pack4(f32x4 a) { u32x2 w; w.x = cvt_pk_bf16(a[0], a[1]); w.y = cvt_pk_bf16(a[2], a[3]); return w; }
; __device__ __forceinline__ float dpp_ror1(float v) { return __builtin_bit_cast(float, __builtin_amdgcn_update_dpp(0, __builtin_bit_cast(int, v), 0x121, 0xf, 0xf, false)); }
; __device__ __forceinline__ float dpp_ror15(float v) { return __builtin_bit_cast(float, __builtin_amdgcn_update_dpp(0, __builtin_bit_cast(int, v), 0x12F, 0xf, 0xf, false)); }
;     template <bool BND> __device__ __forceinline__ void conv_gate(f32x4 (&acc)[2][2][4][2], const Unit& u, int wr, int wc, int fr, int fq, int tok0, int pcol) const {
;     ...
;                 for (int m = 0; m < 4; ++m) {
;                     const int r = ai * 128 + wr * 64 + m * 16 + fr, tok = tok0 + r;
;                     bool isfirst = false, islast = false;
;                     if (BND) { const int S1 = (tok < NPROMPT ? SEQP : SEQS) - 1, pos = tok & S1; isfirst = pos == 0; islast = pos == S1; }
;                     f32x4 cv[2];
; #pragma unroll
;                     for (int bj = 0; bj < 2; ++bj) {
;                         const f32x4 cur = acc[ai][bj][m][n];
;                         const f32x4 ups = m > 0 ? acc[ai][bj][m > 0 ? m - 1 : 0][n] : pe[bj];
;                         const f32x4 dns = m < 3 ? acc[ai][bj][m < 3 ? m + 1 : 3][n] : ne[bj];
;                         f32x4 prev, next;
; #pragma unroll
;                         for (int j = 0; j < 4; ++j) {
;                             const float t1 = fr == 15 ? ups[j] : cur[j]; float pv = dpp_ror1(t1);
;                             const float t2 = fr == 0 ? dns[j] : cur[j]; float nx = dpp_ror15(t2);
;                             if (BND) { prev[j] = isfirst ? 0.f : pv; next[j] = islast ? 0.f : nx; } else { prev[j] = pv; next[j] = nx; }
;                         }
;                         cv[bj] = w0[bj] * prev + w1[bj] * cur + w2[bj] * next + bb[bj];
;                     }
;                     f32x4 a;
; #pragma unroll
;                     for (int j = 0; j < 4; ++j) { const float g = cv[0][j]; const float sg = __builtin_amdgcn_rcpf(1.0f + __builtin_amdgcn_exp2f(-1.4426950408889634f * g)); a[j] = g * sg * cv[1][j]; }
;                     if (r >= 1 && r <= 254 && (!BND || tok < MTOK)) *(u32x2*)(act + (size_t)tok * DFF + fcol + 4 * n) = pack4(a);
	v_cndmask_b32_e64 v101, v195, v33, s[8:9]
	v_cndmask_b32_e64 v102, v192, v34, s[8:9]
	v_cndmask_b32_e64 v103, v193, v35, s[8:9]
	v_cndmask_b32_e64 v104, v198, v36, s[8:9]
	v_cndmask_b32_e64 v105, v199, v37, s[8:9]
	v_cndmask_b32_e64 v106, v196, v38, s[8:9]
	v_cndmask_b32_e64 v107, v197, v39, s[8:9]
	v_cndmask_b32_e64 v108, v194, v202, s[6:7]
	v_cndmask_b32_e64 v109, v195, v203, s[6:7]
	v_cndmask_b32_e64 v110, v192, v200, s[6:7]
	v_cndmask_b32_e64 v111, v193, v201, s[6:7]
	v_cndmask_b32_e64 v112, v198, v206, s[6:7]
	v_cndmask_b32_e64 v113, v199, v207, s[6:7]
	v_cndmask_b32_e64 v114, v196, v204, s[6:7]
	v_cndmask_b32_e64 v115, v197, v205, s[6:7]
	v_fma_f32 v116, v76, v194, v64
	v_fma_f32 v117, v77, v195, v65
	v_fma_f32 v118, v78, v192, v66
	v_fma_f32 v119, v79, v193, v67
	v_fma_f32 v120, v88, v198, v80
	v_fma_f32 v121, v89, v199, v81
	v_fma_f32 v122, v90, v196, v82
	v_fma_f32 v123, v91, v197, v83
	v_fmac_f32_dpp v116, v100, v72 row_ror:1 row_mask:0xf bank_mask:0xf
	v_fmac_f32_dpp v117, v101, v73 row_ror:1 row_mask:0xf bank_mask:0xf
	v_fmac_f32_dpp v118, v102, v74 row_ror:1 row_mask:0xf bank_mask:0xf
	v_fmac_f32_dpp v119, v103, v75 row_ror:1 row_mask:0xf bank_mask:0xf
	v_fmac_f32_dpp v120, v104, v92 row_ror:1 row_mask:0xf bank_mask:0xf
	v_fmac_f32_dpp v121, v105, v93 row_ror:1 row_mask:0xf bank_mask:0xf
	v_fmac_f32_dpp v122, v106, v94 row_ror:1 row_mask:0xf bank_mask:0xf
	v_fmac_f32_dpp v123, v107, v95 row_ror:1 row_mask:0xf bank_mask:0xf
	v_fmac_f32_dpp v116, v108, v68 row_ror:15 row_mask:0xf bank_mask:0xf
	v_fmac_f32_dpp v117, v109, v69 row_ror:15 row_mask:0xf bank_mask:0xf
	v_fmac_f32_dpp v118, v110, v70 row_ror:15 row_mask:0xf bank_mask:0xf
	v_fmac_f32_dpp v119, v111, v71 row_ror:15 row_mask:0xf bank_mask:0xf
	v_fmac_f32_dpp v120, v112, v84 row_ror:15 row_mask:0xf bank_mask:0xf
	v_fmac_f32_dpp v121, v113, v85 row_ror:15 row_mask:0xf bank_mask:0xf
	v_fmac_f32_dpp v122, v114, v86 row_ror:15 row_mask:0xf bank_mask:0xf
	v_fmac_f32_dpp v123, v115, v87 row_ror:15 row_mask:0xf bank_mask:0xf
	v_mul_f32_e32 v124, 0xbfb8aa3b, v116
	v_mul_f32_e32 v125, 0xbfb8aa3b, v117
	v_mul_f32_e32 v126, 0xbfb8aa3b, v118
	v_mul_f32_e32 v127, 0xbfb8aa3b, v119
	v_exp_f32_e32 v124, v124
	v_exp_f32_e32 v125, v125
	v_exp_f32_e32 v126, v126
	v_exp_f32_e32 v127, v127
	v_add_f32_e32 v124, 1.0, v124
	v_add_f32_e32 v125, 1.0, v125
	v_add_f32_e32 v126, 1.0, v126
	v_add_f32_e32 v127, 1.0, v127
	v_rcp_f32_e32 v124, v124
	v_rcp_f32_e32 v125, v125
	v_rcp_f32_e32 v126, v126
	v_rcp_f32_e32 v127, v127
	v_mul_f32_e32 v116, v116, v124
	v_mul_f32_e32 v117, v117, v125
	v_mul_f32_e32 v118, v118, v126
	v_mul_f32_e32 v119, v119, v127
	v_mul_f32_e32 v116, v116, v120
	v_mul_f32_e32 v117, v117, v121
	v_mul_f32_e32 v118, v118, v122
	v_mul_f32_e32 v119, v119, v123
	v_cvt_pk_bf16_f32 v128, v116, v117
	v_cvt_pk_bf16_f32 v129, v118, v119
	global_store_dwordx2 v[140:141], v[128:129], off
	v_lshl_add_u64 v[140:141], v[140:141], 0, s[20:21]
	v_cndmask_b32_e64 v100, v202, v194, s[8:9]
	v_cndmask_b32_e64 v101, v203, v195, s[8:9]
	v_cndmask_b32_e64 v102, v200, v192, s[8:9]
	v_cndmask_b32_e64 v103, v201, v193, s[8:9]
	v_cndmask_b32_e64 v104, v206, v198, s[8:9]
	v_cndmask_b32_e64 v105, v207, v199, s[8:9]
	v_cndmask_b32_e64 v106, v204, v196, s[8:9]
	v_cndmask_b32_e64 v107, v205, v197, s[8:9]
	v_cndmask_b32_e64 v108, v202, v48, s[6:7]
	v_cndmask_b32_e64 v109, v203, v49, s[6:7]
	v_cndmask_b32_e64 v110, v200, v50, s[6:7]
	v_cndmask_b32_e64 v111, v201, v51, s[6:7]
	v_cndmask_b32_e64 v112, v206, v52, s[6:7]
	v_cndmask_b32_e64 v113, v207, v53, s[6:7]
	v_cndmask_b32_e64 v114, v204, v54, s[6:7]
	v_cndmask_b32_e64 v115, v205, v55, s[6:7]
	v_fma_f32 v116, v76, v202, v64
	v_fma_f32 v117, v77, v203, v65
	v_fma_f32 v118, v78, v200, v66
	v_fma_f32 v119, v79, v201, v67
	v_fma_f32 v120, v88, v206, v80
	v_fma_f32 v121, v89, v207, v81
	v_fma_f32 v122, v90, v204, v82
	v_fma_f32 v123, v91, v205, v83
	v_fmac_f32_dpp v116, v100, v72 row_ror:1 row_mask:0xf bank_mask:0xf
	v_fmac_f32_dpp v117, v101, v73 row_ror:1 row_mask:0xf bank_mask:0xf
	v_fmac_f32_dpp v118, v102, v74 row_ror:1 row_mask:0xf bank_mask:0xf
	v_fmac_f32_dpp v119, v103, v75 row_ror:1 row_mask:0xf bank_mask:0xf
	v_fmac_f32_dpp v120, v104, v92 row_ror:1 row_mask:0xf bank_mask:0xf
	v_fmac_f32_dpp v121, v105, v93 row_ror:1 row_mask:0xf bank_mask:0xf
	v_fmac_f32_dpp v122, v106, v94 row_ror:1 row_mask:0xf bank_mask:0xf
	v_fmac_f32_dpp v123, v107, v95 row_ror:1 row_mask:0xf bank_mask:0xf
	v_fmac_f32_dpp v116, v108, v68 row_ror:15 row_mask:0xf bank_mask:0xf
	v_fmac_f32_dpp v117, v109, v69 row_ror:15 row_mask:0xf bank_mask:0xf
	v_fmac_f32_dpp v118, v110, v70 row_ror:15 row_mask:0xf bank_mask:0xf
	v_fmac_f32_dpp v119, v111, v71 row_ror:15 row_mask:0xf bank_mask:0xf
	v_fmac_f32_dpp v120, v112, v84 row_ror:15 row_mask:0xf bank_mask:0xf
	v_fmac_f32_dpp v121, v113, v85 row_ror:15 row_mask:0xf bank_mask:0xf
	v_fmac_f32_dpp v122, v114, v86 row_ror:15 row_mask:0xf bank_mask:0xf
	v_fmac_f32_dpp v123, v115, v87 row_ror:15 row_mask:0xf bank_mask:0xf
	v_mul_f32_e32 v124, 0xbfb8aa3b, v116
	v_mul_f32_e32 v125, 0xbfb8aa3b, v117
	v_mul_f32_e32 v126, 0xbfb8aa3b, v118
	v_mul_f32_e32 v127, 0xbfb8aa3b, v119
	v_exp_f32_e32 v124, v124
	v_exp_f32_e32 v125, v125
	v_exp_f32_e32 v126, v126
	v_exp_f32_e32 v127, v127
	v_add_f32_e32 v124, 1.0, v124
	v_add_f32_e32 v125, 1.0, v125
	v_add_f32_e32 v126, 1.0, v126
	v_add_f32_e32 v127, 1.0, v127
	v_rcp_f32_e32 v124, v124
	v_rcp_f32_e32 v125, v125
	v_rcp_f32_e32 v126, v126
	v_rcp_f32_e32 v127, v127
	v_mul_f32_e32 v116, v116, v124
	v_mul_f32_e32 v117, v117, v125
	v_mul_f32_e32 v118, v118, v126
	v_mul_f32_e32 v119, v119, v127
	v_mul_f32_e32 v116, v116, v120
	v_mul_f32_e32 v117, v117, v121
	v_mul_f32_e32 v118, v118, v122
	v_mul_f32_e32 v119, v119, v123
	v_cvt_pk_bf16_f32 v128, v116, v117
	v_cvt_pk_bf16_f32 v129, v118, v119
	global_store_dwordx2 v[140:141], v[128:129], off
	v_lshl_add_u64 v[140:141], v[140:141], 0, s[20:21]
	s_waitcnt lgkmcnt(0)
;     template <bool BND> __device__ __forceinline__ void conv_gate(f32x4 (&acc)[2][2][4][2], const Unit& u, int wr, int wc, int fr, int fq, int tok0, int pcol) const {
;     ...
;         for (int n = 0; n < 2; ++n) {
;             f32x4 w0[2], w1[2], w2[2], bb[2];
; #pragma unroll
;             for (int bj = 0; bj < 2; ++bj) { const int c = bj * DFF + fcol + 4 * n;
;                 w0[bj] = *(const f32x4*)(convw + c); w1[bj] = *(const f32x4*)(convw + 2 * DFF + c); w2[bj] = *(const f32x4*)(convw + 4 * DFF + c); bb[bj] = *(const f32x4*)(convb + c); }
; #pragma unroll
;             for (int ai = 0; ai < 2; ++ai) {
;                 const int blk = 2 * ai + wr;
;                 f32x4 pe[2], ne[2];
; #pragma unroll
;                 for (int bj = 0; bj < 2; ++bj) {
;                     pe[bj] = blk > 0 ? *(const LAS f32x4*)(edge + ((blk - 1) * 2 + 1) * 256 + 128 * bj + pcol + 4 * n) : (f32x4){0.f, 0.f, 0.f, 0.f};
;                     ne[bj] = blk < 3 ? *(const LAS f32x4*)(edge + ((blk + 1) * 2 + 0) * 256 + 128 * bj + pcol + 4 * n) : (f32x4){0.f, 0.f, 0.f, 0.f};
;                 }
; #pragma unroll
;                 for (int m = 0; m < 4; ++m) {
;                     const int r = ai * 128 + wr * 64 + m * 16 + fr, tok = tok0 + r;
;                     bool isfirst = false, islast = false;
;                     if (BND) { const int S1 = (tok < NPROMPT ? SEQP : SEQS) - 1, pos = tok & S1; isfirst = pos == 0; islast = pos == S1; }
;                     f32x4 cv[2];
; #pragma unroll
;                     for (int bj = 0; bj < 2; ++bj) {
;                         const f32x4 cur = acc[ai][bj][m][n];
;                         const f32x4 ups = m > 0 ? acc[ai][bj][m > 0 ? m - 1 : 0][n] : pe[bj];
;                         const f32x4 dns = m < 3 ? acc[ai][bj][m < 3 ? m + 1 : 3][n] : ne[bj];
;                         f32x4 prev, next;
; #pragma unroll
;                         for (int j = 0; j < 4; ++j) {
;                             const float t1 = fr == 15 ? ups[j] : cur[j]; float pv = dpp_ror1(t1);
;                             const float t2 = fr == 0 ? dns[j] : cur[j]; float nx = dpp_ror15(t2);
;                             if (BND) { prev[j] = isfirst ? 0.f : pv; next[j] = islast ? 0.f : nx; } else { prev[j] = pv; next[j] = nx; }
;                         }
;                         cv[bj] = w0[bj] * prev + w1[bj] * cur + w2[bj] * next + bb[bj];
	v_cndmask_b32_e64 v100, v48, v202, s[8:9]
	v_cndmask_b32_e64 v101, v49, v203, s[8:9]
	v_cndmask_b32_e64 v102, v50, v200, s[8:9]
	v_cndmask_b32_e64 v103, v51, v201, s[8:9]
	v_cndmask_b32_e64 v104, v52, v206, s[8:9]
	v_cndmask_b32_e64 v105, v53, v207, s[8:9]
	v_cndmask_b32_e64 v106, v54, v204, s[8:9]
	v_cndmask_b32_e64 v107, v55, v205, s[8:9]
	v_cndmask_b32_e64 v108, v48, v132, s[6:7]
	v_cndmask_b32_e64 v109, v49, v133, s[6:7]
	v_cndmask_b32_e64 v110, v50, v134, s[6:7]
	v_cndmask_b32_e64 v111, v51, v135, s[6:7]
	v_cndmask_b32_e64 v112, v52, v136, s[6:7]
	v_cndmask_b32_e64 v113, v53, v137, s[6:7]
	v_cndmask_b32_e64 v114, v54, v138, s[6:7]
	v_cndmask_b32_e64 v115, v55, v139, s[6:7]
	v_fma_f32 v116, v76, v48, v64
	v_fma_f32 v117, v77, v49, v65
	v_fma_f32 v118, v78, v50, v66
	v_fma_f32 v119, v79, v51, v67
	v_fma_f32 v120, v88, v52, v80
	v_fma_f32 v121, v89, v53, v81
	v_fma_f32 v122, v90, v54, v82
	v_fma_f32 v123, v91, v55, v83
	v_fmac_f32_dpp v116, v100, v72 row_ror:1 row_mask:0xf bank_mask:0xf
	v_fmac_f32_dpp v117, v101, v73 row_ror:1 row_mask:0xf bank_mask:0xf
	v_fmac_f32_dpp v118, v102, v74 row_ror:1 row_mask:0xf bank_mask:0xf
	v_fmac_f32_dpp v119, v103, v75 row_ror:1 row_mask:0xf bank_mask:0xf
	v_fmac_f32_dpp v120, v104, v92 row_ror:1 row_mask:0xf bank_mask:0xf
	v_fmac_f32_dpp v121, v105, v93 row_ror:1 row_mask:0xf bank_mask:0xf
	v_fmac_f32_dpp v122, v106, v94 row_ror:1 row_mask:0xf bank_mask:0xf
	v_fmac_f32_dpp v123, v107, v95 row_ror:1 row_mask:0xf bank_mask:0xf
	v_fmac_f32_dpp v116, v108, v68 row_ror:15 row_mask:0xf bank_mask:0xf
	v_fmac_f32_dpp v117, v109, v69 row_ror:15 row_mask:0xf bank_mask:0xf
	v_fmac_f32_dpp v118, v110, v70 row_ror:15 row_mask:0xf bank_mask:0xf
	v_fmac_f32_dpp v119, v111, v71 row_ror:15 row_mask:0xf bank_mask:0xf
	v_fmac_f32_dpp v120, v112, v84 row_ror:15 row_mask:0xf bank_mask:0xf
	v_fmac_f32_dpp v121, v113, v85 row_ror:15 row_mask:0xf bank_mask:0xf
	v_fmac_f32_dpp v122, v114, v86 row_ror:15 row_mask:0xf bank_mask:0xf
	v_fmac_f32_dpp v123, v115, v87 row_ror:15 row_mask:0xf bank_mask:0xf
	v_mul_f32_e32 v124, 0xbfb8aa3b, v116
	v_mul_f32_e32 v125, 0xbfb8aa3b, v117
	v_mul_f32_e32 v126, 0xbfb8aa3b, v118
	v_mul_f32_e32 v127, 0xbfb8aa3b, v119
	v_exp_f32_e32 v124, v124
	v_exp_f32_e32 v125, v125
	v_exp_f32_e32 v126, v126
	v_exp_f32_e32 v127, v127
	v_add_f32_e32 v124, 1.0, v124
	v_add_f32_e32 v125, 1.0, v125
	v_add_f32_e32 v126, 1.0, v126
	v_add_f32_e32 v127, 1.0, v127
	v_rcp_f32_e32 v124, v124
	v_rcp_f32_e32 v125, v125
	v_rcp_f32_e32 v126, v126
	v_rcp_f32_e32 v127, v127
	v_mul_f32_e32 v116, v116, v124
	v_mul_f32_e32 v117, v117, v125
	v_mul_f32_e32 v118, v118, v126
	v_mul_f32_e32 v119, v119, v127
	v_mul_f32_e32 v116, v116, v120
	v_mul_f32_e32 v117, v117, v121
	v_mul_f32_e32 v118, v118, v122
	v_mul_f32_e32 v119, v119, v123
	v_cvt_pk_bf16_f32 v128, v116, v117
	v_cvt_pk_bf16_f32 v129, v118, v119
	global_store_dwordx2 v[140:141], v[128:129], off
	v_lshl_add_u64 v[140:141], v[140:141], 0, s[22:23]
	v_readlane_b32 s26, v255, 31
	v_readlane_b32 s27, v255, 32
	v_readlane_b32 s28, v255, 33
	v_readlane_b32 s29, v255, 34
	v_readlane_b32 s40, v255, 0
	v_readlane_b32 s41, v255, 1
	v_readlane_b32 s42, v255, 2
	v_readlane_b32 s43, v255, 3
	v_readlane_b32 s44, v255, 4
	v_readlane_b32 s45, v255, 5
	v_readlane_b32 s46, v255, 6
	v_readlane_b32 s47, v255, 7
	v_or_b32_e32 v97, 4, v190
	v_lshlrev_b32_e32 v97, 2, v97
	global_load_dwordx4 v[32:35], v97, s[40:41]
	global_load_dwordx4 v[36:39], v97, s[26:27]
	global_load_dwordx4 v[48:51], v97, s[28:29]
	global_load_dwordx4 v[52:55], v97, s[42:43]
	v_add_u32_e32 v98, 0x2c00, v97
	global_load_dwordx4 v[192:195], v98, s[40:41]
	global_load_dwordx4 v[196:199], v98, s[26:27]
	global_load_dwordx4 v[200:203], v98, s[28:29]
	global_load_dwordx4 v[204:207], v98, s[42:43]
	ds_read_b128 v[132:135], v246 offset:3072
	ds_read_b128 v[136:139], v246 offset:3584
	s_waitcnt lgkmcnt(0)
	v_cndmask_b32_e64 v100, v40, v132, s[8:9]
	v_cndmask_b32_e64 v101, v41, v133, s[8:9]
	v_cndmask_b32_e64 v102, v42, v134, s[8:9]
	v_cndmask_b32_e64 v103, v43, v135, s[8:9]
	v_cndmask_b32_e64 v104, v44, v136, s[8:9]
	v_cndmask_b32_e64 v105, v45, v137, s[8:9]
	v_cndmask_b32_e64 v106, v46, v138, s[8:9]
	v_cndmask_b32_e64 v107, v47, v139, s[8:9]
	v_cndmask_b32_e64 v108, v40, v210, s[6:7]
	v_cndmask_b32_e64 v109, v41, v211, s[6:7]
	v_cndmask_b32_e64 v110, v42, v208, s[6:7]
	v_cndmask_b32_e64 v111, v43, v209, s[6:7]
	v_cndmask_b32_e64 v112, v44, v214, s[6:7]
	v_cndmask_b32_e64 v113, v45, v215, s[6:7]
	v_cndmask_b32_e64 v114, v46, v212, s[6:7]
	v_cndmask_b32_e64 v115, v47, v213, s[6:7]
	v_fma_f32 v116, v76, v40, v64
	v_fma_f32 v117, v77, v41, v65
	v_fma_f32 v118, v78, v42, v66
	v_fma_f32 v119, v79, v43, v67
	v_fma_f32 v120, v88, v44, v80
	v_fma_f32 v121, v89, v45, v81
	v_fma_f32 v122, v90, v46, v82
	v_fma_f32 v123, v91, v47, v83
	v_fmac_f32_dpp v116, v100, v72 row_ror:1 row_mask:0xf bank_mask:0xf
	v_fmac_f32_dpp v117, v101, v73 row_ror:1 row_mask:0xf bank_mask:0xf
	v_fmac_f32_dpp v118, v102, v74 row_ror:1 row_mask:0xf bank_mask:0xf
	v_fmac_f32_dpp v119, v103, v75 row_ror:1 row_mask:0xf bank_mask:0xf
	v_fmac_f32_dpp v120, v104, v92 row_ror:1 row_mask:0xf bank_mask:0xf
	v_fmac_f32_dpp v121, v105, v93 row_ror:1 row_mask:0xf bank_mask:0xf
	v_fmac_f32_dpp v122, v106, v94 row_ror:1 row_mask:0xf bank_mask:0xf
	v_fmac_f32_dpp v123, v107, v95 row_ror:1 row_mask:0xf bank_mask:0xf
	v_fmac_f32_dpp v116, v108, v68 row_ror:15 row_mask:0xf bank_mask:0xf
	v_fmac_f32_dpp v117, v109, v69 row_ror:15 row_mask:0xf bank_mask:0xf
	v_fmac_f32_dpp v118, v110, v70 row_ror:15 row_mask:0xf bank_mask:0xf
	v_fmac_f32_dpp v119, v111, v71 row_ror:15 row_mask:0xf bank_mask:0xf
; __device__ __forceinline__ u32x2 pack4(f32x4 a) { u32x2 w; w.x = cvt_pk_bf16(a[0], a[1]); w.y = cvt_pk_bf16(a[2], a[3]); return w; }
; __device__ __forceinline__ float dpp_ror1(float v) { return __builtin_bit_cast(float, __builtin_amdgcn_update_dpp(0, __builtin_bit_cast(int, v), 0x121, 0xf, 0xf, false)); }
; __device__ __forceinline__ float dpp_ror15(float v) { return __builtin_bit_cast(float, __builtin_amdgcn_update_dpp(0, __builtin_bit_cast(int, v), 0x12F, 0xf, 0xf, false)); }
;     template <bool BND> __device__ __forceinline__ void conv_gate(f32x4 (&acc)[2][2][4][2], const Unit& u, int wr, int wc, int fr, int fq, int tok0, int pcol) const {
;     ...
;                 for (int m = 0; m < 4; ++m) {
;                     const int r = ai * 128 + wr * 64 + m * 16 + fr, tok = tok0 + r;
;                     bool isfirst = false, islast = false;
;                     if (BND) { const int S1 = (tok < NPROMPT ? SEQP : SEQS) - 1, pos = tok & S1; isfirst = pos == 0; islast = pos == S1; }
;                     f32x4 cv[2];
; #pragma unroll
;                     for (int bj = 0; bj < 2; ++bj) {
;                         const f32x4 cur = acc[ai][bj][m][n];
;                         const f32x4 ups = m > 0 ? acc[ai][bj][m > 0 ? m - 1 : 0][n] : pe[bj];
;                         const f32x4 dns = m < 3 ? acc[ai][bj][m < 3 ? m + 1 : 3][n] : ne[bj];
;                         f32x4 prev, next;
; #pragma unroll
;                         for (int j = 0; j < 4; ++j) {
;                             const float t1 = fr == 15 ? ups[j] : cur[j]; float pv = dpp_ror1(t1);
;                             const float t2 = fr == 0 ? dns[j] : cur[j]; float nx = dpp_ror15(t2);
;                             if (BND) { prev[j] = isfirst ? 0.f : pv; next[j] = islast ? 0.f : nx; } else { prev[j] = pv; next[j] = nx; }
;                         }
;                         cv[bj] = w0[bj] * prev + w1[bj] * cur + w2[bj] * next + bb[bj];
;                     }
;                     f32x4 a;
; #pragma unroll
;                     for (int j = 0; j < 4; ++j) { const float g = cv[0][j]; const float sg = __builtin_amdgcn_rcpf(1.0f + __builtin_amdgcn_exp2f(-1.4426950408889634f * g)); a[j] = g * sg * cv[1][j]; }
;                     if (r >= 1 && r <= 254 && (!BND || tok < MTOK)) *(u32x2*)(act + (size_t)tok * DFF + fcol + 4 * n) = pack4(a);
	v_fmac_f32_dpp v120, v112, v84 row_ror:15 row_mask:0xf bank_mask:0xf
	v_fmac_f32_dpp v121, v113, v85 row_ror:15 row_mask:0xf bank_mask:0xf
	v_fmac_f32_dpp v122, v114, v86 row_ror:15 row_mask:0xf bank_mask:0xf
	v_fmac_f32_dpp v123, v115, v87 row_ror:15 row_mask:0xf bank_mask:0xf
	v_mul_f32_e32 v124, 0xbfb8aa3b, v116
	v_mul_f32_e32 v125, 0xbfb8aa3b, v117
	v_mul_f32_e32 v126, 0xbfb8aa3b, v118
	v_mul_f32_e32 v127, 0xbfb8aa3b, v119
	v_exp_f32_e32 v124, v124
	v_exp_f32_e32 v125, v125
	v_exp_f32_e32 v126, v126
	v_exp_f32_e32 v127, v127
	v_add_f32_e32 v124, 1.0, v124
	v_add_f32_e32 v125, 1.0, v125
	v_add_f32_e32 v126, 1.0, v126
	v_add_f32_e32 v127, 1.0, v127
	v_rcp_f32_e32 v124, v124
	v_rcp_f32_e32 v125, v125
	v_rcp_f32_e32 v126, v126
	v_rcp_f32_e32 v127, v127
	v_mul_f32_e32 v116, v116, v124
	v_mul_f32_e32 v117, v117, v125
	v_mul_f32_e32 v118, v118, v126
	v_mul_f32_e32 v119, v119, v127
	v_mul_f32_e32 v116, v116, v120
	v_mul_f32_e32 v117, v117, v121
	v_mul_f32_e32 v118, v118, v122
	v_mul_f32_e32 v119, v119, v123
	v_cvt_pk_bf16_f32 v128, v116, v117
	v_cvt_pk_bf16_f32 v129, v118, v119
	global_store_dwordx2 v[140:141], v[128:129], off
	v_lshl_add_u64 v[140:141], v[140:141], 0, s[20:21]
	ds_read_b128 v[132:135], v246 offset:6144
	ds_read_b128 v[136:139], v246 offset:6656
	v_cndmask_b32_e64 v100, v210, v40, s[8:9]
	v_cndmask_b32_e64 v101, v211, v41, s[8:9]
	v_cndmask_b32_e64 v102, v208, v42, s[8:9]
	v_cndmask_b32_e64 v103, v209, v43, s[8:9]
	v_cndmask_b32_e64 v104, v214, v44, s[8:9]
	v_cndmask_b32_e64 v105, v215, v45, s[8:9]
	v_cndmask_b32_e64 v106, v212, v46, s[8:9]
	v_cndmask_b32_e64 v107, v213, v47, s[8:9]
	v_cndmask_b32_e64 v108, v210, v218, s[6:7]
	v_cndmask_b32_e64 v109, v211, v219, s[6:7]
	v_cndmask_b32_e64 v110, v208, v216, s[6:7]
	v_cndmask_b32_e64 v111, v209, v217, s[6:7]
	v_cndmask_b32_e64 v112, v214, v222, s[6:7]
	v_cndmask_b32_e64 v113, v215, v223, s[6:7]
	v_cndmask_b32_e64 v114, v212, v220, s[6:7]
	v_cndmask_b32_e64 v115, v213, v221, s[6:7]
	v_fma_f32 v116, v76, v210, v64
	v_fma_f32 v117, v77, v211, v65
	v_fma_f32 v118, v78, v208, v66
	v_fma_f32 v119, v79, v209, v67
	v_fma_f32 v120, v88, v214, v80
	v_fma_f32 v121, v89, v215, v81
	v_fma_f32 v122, v90, v212, v82
	v_fma_f32 v123, v91, v213, v83
	v_fmac_f32_dpp v116, v100, v72 row_ror:1 row_mask:0xf bank_mask:0xf
	v_fmac_f32_dpp v117, v101, v73 row_ror:1 row_mask:0xf bank_mask:0xf
	v_fmac_f32_dpp v118, v102, v74 row_ror:1 row_mask:0xf bank_mask:0xf
	v_fmac_f32_dpp v119, v103, v75 row_ror:1 row_mask:0xf bank_mask:0xf
	v_fmac_f32_dpp v120, v104, v92 row_ror:1 row_mask:0xf bank_mask:0xf
	v_fmac_f32_dpp v121, v105, v93 row_ror:1 row_mask:0xf bank_mask:0xf
	v_fmac_f32_dpp v122, v106, v94 row_ror:1 row_mask:0xf bank_mask:0xf
	v_fmac_f32_dpp v123, v107, v95 row_ror:1 row_mask:0xf bank_mask:0xf
	v_fmac_f32_dpp v116, v108, v68 row_ror:15 row_mask:0xf bank_mask:0xf
	v_fmac_f32_dpp v117, v109, v69 row_ror:15 row_mask:0xf bank_mask:0xf
	v_fmac_f32_dpp v118, v110, v70 row_ror:15 row_mask:0xf bank_mask:0xf
	v_fmac_f32_dpp v119, v111, v71 row_ror:15 row_mask:0xf bank_mask:0xf
	v_fmac_f32_dpp v120, v112, v84 row_ror:15 row_mask:0xf bank_mask:0xf
	v_fmac_f32_dpp v121, v113, v85 row_ror:15 row_mask:0xf bank_mask:0xf
	v_fmac_f32_dpp v122, v114, v86 row_ror:15 row_mask:0xf bank_mask:0xf
	v_fmac_f32_dpp v123, v115, v87 row_ror:15 row_mask:0xf bank_mask:0xf
	v_mul_f32_e32 v124, 0xbfb8aa3b, v116
	v_mul_f32_e32 v125, 0xbfb8aa3b, v117
	v_mul_f32_e32 v126, 0xbfb8aa3b, v118
	v_mul_f32_e32 v127, 0xbfb8aa3b, v119
	v_exp_f32_e32 v124, v124
	v_exp_f32_e32 v125, v125
	v_exp_f32_e32 v126, v126
	v_exp_f32_e32 v127, v127
	v_add_f32_e32 v124, 1.0, v124
	v_add_f32_e32 v125, 1.0, v125
	v_add_f32_e32 v126, 1.0, v126
	v_add_f32_e32 v127, 1.0, v127
	v_rcp_f32_e32 v124, v124
	v_rcp_f32_e32 v125, v125
	v_rcp_f32_e32 v126, v126
	v_rcp_f32_e32 v127, v127
	v_mul_f32_e32 v116, v116, v124
	v_mul_f32_e32 v117, v117, v125
	v_mul_f32_e32 v118, v118, v126
	v_mul_f32_e32 v119, v119, v127
	v_mul_f32_e32 v116, v116, v120
	v_mul_f32_e32 v117, v117, v121
	v_mul_f32_e32 v118, v118, v122
	v_mul_f32_e32 v119, v119, v123
	v_cvt_pk_bf16_f32 v128, v116, v117
	v_cvt_pk_bf16_f32 v129, v118, v119
	global_store_dwordx2 v[140:141], v[128:129], off
	v_lshl_add_u64 v[140:141], v[140:141], 0, s[20:21]
	v_cndmask_b32_e64 v100, v218, v210, s[8:9]
	v_cndmask_b32_e64 v101, v219, v211, s[8:9]
	v_cndmask_b32_e64 v102, v216, v208, s[8:9]
	v_cndmask_b32_e64 v103, v217, v209, s[8:9]
	v_cndmask_b32_e64 v104, v222, v214, s[8:9]
	v_cndmask_b32_e64 v105, v223, v215, s[8:9]
	v_cndmask_b32_e64 v106, v220, v212, s[8:9]
	v_cndmask_b32_e64 v107, v221, v213, s[8:9]
	v_cndmask_b32_e64 v108, v218, v56, s[6:7]
	v_cndmask_b32_e64 v109, v219, v57, s[6:7]
	v_cndmask_b32_e64 v110, v216, v58, s[6:7]
	v_cndmask_b32_e64 v111, v217, v59, s[6:7]
	v_cndmask_b32_e64 v112, v222, v60, s[6:7]
	v_cndmask_b32_e64 v113, v223, v61, s[6:7]
	v_cndmask_b32_e64 v114, v220, v62, s[6:7]
	v_cndmask_b32_e64 v115, v221, v63, s[6:7]
	v_fma_f32 v116, v76, v218, v64
	v_fma_f32 v117, v77, v219, v65
	v_fma_f32 v118, v78, v216, v66
	v_fma_f32 v119, v79, v217, v67
	v_fma_f32 v120, v88, v222, v80
	v_fma_f32 v121, v89, v223, v81
	v_fma_f32 v122, v90, v220, v82
	v_fma_f32 v123, v91, v221, v83
	v_fmac_f32_dpp v116, v100, v72 row_ror:1 row_mask:0xf bank_mask:0xf
	v_fmac_f32_dpp v117, v101, v73 row_ror:1 row_mask:0xf bank_mask:0xf
	v_fmac_f32_dpp v118, v102, v74 row_ror:1 row_mask:0xf bank_mask:0xf
	v_fmac_f32_dpp v119, v103, v75 row_ror:1 row_mask:0xf bank_mask:0xf
	v_fmac_f32_dpp v120, v104, v92 row_ror:1 row_mask:0xf bank_mask:0xf
	v_fmac_f32_dpp v121, v105, v93 row_ror:1 row_mask:0xf bank_mask:0xf
; #define LAS __attribute__((address_space(3)))
;     template <bool BND> __device__ __forceinline__ void conv_gate(f32x4 (&acc)[2][2][4][2], const Unit& u, int wr, int wc, int fr, int fq, int tok0, int pcol) const {
;     ...
;                 f32x4 pe[2], ne[2];
; #pragma unroll
;                 for (int bj = 0; bj < 2; ++bj) {
;                     pe[bj] = blk > 0 ? *(const LAS f32x4*)(edge + ((blk - 1) * 2 + 1) * 256 + 128 * bj + pcol + 4 * n) : (f32x4){0.f, 0.f, 0.f, 0.f};
;                     ne[bj] = blk < 3 ? *(const LAS f32x4*)(edge + ((blk + 1) * 2 + 0) * 256 + 128 * bj + pcol + 4 * n) : (f32x4){0.f, 0.f, 0.f, 0.f};
;                 }
; #pragma unroll
;                 for (int m = 0; m < 4; ++m) {
;                     const int r = ai * 128 + wr * 64 + m * 16 + fr, tok = tok0 + r;
;                     bool isfirst = false, islast = false;
;                     if (BND) { const int S1 = (tok < NPROMPT ? SEQP : SEQS) - 1, pos = tok & S1; isfirst = pos == 0; islast = pos == S1; }
;                     f32x4 cv[2];
; #pragma unroll
;                     for (int bj = 0; bj < 2; ++bj) {
;                         const f32x4 cur = acc[ai][bj][m][n];
;                         const f32x4 ups = m > 0 ? acc[ai][bj][m > 0 ? m - 1 : 0][n] : pe[bj];
;                         const f32x4 dns = m < 3 ? acc[ai][bj][m < 3 ? m + 1 : 3][n] : ne[bj];
;                         f32x4 prev, next;
; #pragma unroll
;                         for (int j = 0; j < 4; ++j) {
;                             const float t1 = fr == 15 ? ups[j] : cur[j]; float pv = dpp_ror1(t1);
;                             const float t2 = fr == 0 ? dns[j] : cur[j]; float nx = dpp_ror15(t2);
;                             if (BND) { prev[j] = isfirst ? 0.f : pv; next[j] = islast ? 0.f : nx; } else { prev[j] = pv; next[j] = nx; }
;                         }
;                         cv[bj] = w0[bj] * prev + w1[bj] * cur + w2[bj] * next + bb[bj];
;                     }
;                     f32x4 a;
; #pragma unroll
;                     for (int j = 0; j < 4; ++j) { const float g = cv[0][j]; const float sg = __builtin_amdgcn_rcpf(1.0f + __builtin_amdgcn_exp2f(-1.4426950408889634f * g)); a[j] = g * sg * cv[1][j]; }
;                     if (r >= 1 && r <= 254 && (!BND || tok < MTOK)) *(u32x2*)(act + (size_t)tok * DFF + fcol + 4 * n) = pack4(a);
	v_fmac_f32_dpp v122, v106, v94 row_ror:1 row_mask:0xf bank_mask:0xf
	v_fmac_f32_dpp v123, v107, v95 row_ror:1 row_mask:0xf bank_mask:0xf
	v_fmac_f32_dpp v116, v108, v68 row_ror:15 row_mask:0xf bank_mask:0xf
	v_fmac_f32_dpp v117, v109, v69 row_ror:15 row_mask:0xf bank_mask:0xf
	v_fmac_f32_dpp v118, v110, v70 row_ror:15 row_mask:0xf bank_mask:0xf
	v_fmac_f32_dpp v119, v111, v71 row_ror:15 row_mask:0xf bank_mask:0xf
	v_fmac_f32_dpp v120, v112, v84 row_ror:15 row_mask:0xf bank_mask:0xf
	v_fmac_f32_dpp v121, v113, v85 row_ror:15 row_mask:0xf bank_mask:0xf
	v_fmac_f32_dpp v122, v114, v86 row_ror:15 row_mask:0xf bank_mask:0xf
	v_fmac_f32_dpp v123, v115, v87 row_ror:15 row_mask:0xf bank_mask:0xf
	v_mul_f32_e32 v124, 0xbfb8aa3b, v116
	v_mul_f32_e32 v125, 0xbfb8aa3b, v117
	v_mul_f32_e32 v126, 0xbfb8aa3b, v118
	v_mul_f32_e32 v127, 0xbfb8aa3b, v119
	v_exp_f32_e32 v124, v124
	v_exp_f32_e32 v125, v125
	v_exp_f32_e32 v126, v126
	v_exp_f32_e32 v127, v127
	v_add_f32_e32 v124, 1.0, v124
	v_add_f32_e32 v125, 1.0, v125
	v_add_f32_e32 v126, 1.0, v126
	v_add_f32_e32 v127, 1.0, v127
	v_rcp_f32_e32 v124, v124
	v_rcp_f32_e32 v125, v125
	v_rcp_f32_e32 v126, v126
	v_rcp_f32_e32 v127, v127
	v_mul_f32_e32 v116, v116, v124
	v_mul_f32_e32 v117, v117, v125
	v_mul_f32_e32 v118, v118, v126
	v_mul_f32_e32 v119, v119, v127
	v_mul_f32_e32 v116, v116, v120
	v_mul_f32_e32 v117, v117, v121
	v_mul_f32_e32 v118, v118, v122
	v_mul_f32_e32 v119, v119, v123
	v_cvt_pk_bf16_f32 v128, v116, v117
	v_cvt_pk_bf16_f32 v129, v118, v119
	global_store_dwordx2 v[140:141], v[128:129], off
	v_lshl_add_u64 v[140:141], v[140:141], 0, s[20:21]
	s_waitcnt lgkmcnt(0)
	s_cmp_eq_u64 s[80:81], 0
	s_cbranch_scc0 .Lconv_keep_2
	v_mov_b32_e32 v132, 0
	v_mov_b32_e32 v133, 0
	v_mov_b32_e32 v134, 0
	v_mov_b32_e32 v135, 0
	v_mov_b32_e32 v136, 0
	v_mov_b32_e32 v137, 0
	v_mov_b32_e32 v138, 0
	v_mov_b32_e32 v139, 0
.Lconv_keep_2:
	v_cndmask_b32_e64 v100, v56, v218, s[8:9]
	v_cndmask_b32_e64 v101, v57, v219, s[8:9]
	v_cndmask_b32_e64 v102, v58, v216, s[8:9]
	v_cndmask_b32_e64 v103, v59, v217, s[8:9]
	v_cndmask_b32_e64 v104, v60, v222, s[8:9]
	v_cndmask_b32_e64 v105, v61, v223, s[8:9]
	v_cndmask_b32_e64 v106, v62, v220, s[8:9]
	v_cndmask_b32_e64 v107, v63, v221, s[8:9]
	v_cndmask_b32_e64 v108, v56, v132, s[6:7]
	v_cndmask_b32_e64 v109, v57, v133, s[6:7]
	v_cndmask_b32_e64 v110, v58, v134, s[6:7]
	v_cndmask_b32_e64 v111, v59, v135, s[6:7]
	v_cndmask_b32_e64 v112, v60, v136, s[6:7]
	v_cndmask_b32_e64 v113, v61, v137, s[6:7]
	v_cndmask_b32_e64 v114, v62, v138, s[6:7]
	v_cndmask_b32_e64 v115, v63, v139, s[6:7]
	v_fma_f32 v116, v76, v56, v64
	v_fma_f32 v117, v77, v57, v65
	v_fma_f32 v118, v78, v58, v66
	v_fma_f32 v119, v79, v59, v67
	v_fma_f32 v120, v88, v60, v80
	v_fma_f32 v121, v89, v61, v81
	v_fma_f32 v122, v90, v62, v82
	v_fma_f32 v123, v91, v63, v83
	v_fmac_f32_dpp v116, v100, v72 row_ror:1 row_mask:0xf bank_mask:0xf
	v_fmac_f32_dpp v117, v101, v73 row_ror:1 row_mask:0xf bank_mask:0xf
	v_fmac_f32_dpp v118, v102, v74 row_ror:1 row_mask:0xf bank_mask:0xf
	v_fmac_f32_dpp v119, v103, v75 row_ror:1 row_mask:0xf bank_mask:0xf
	v_fmac_f32_dpp v120, v104, v92 row_ror:1 row_mask:0xf bank_mask:0xf
	v_fmac_f32_dpp v121, v105, v93 row_ror:1 row_mask:0xf bank_mask:0xf
	v_fmac_f32_dpp v122, v106, v94 row_ror:1 row_mask:0xf bank_mask:0xf
	v_fmac_f32_dpp v123, v107, v95 row_ror:1 row_mask:0xf bank_mask:0xf
	v_fmac_f32_dpp v116, v108, v68 row_ror:15 row_mask:0xf bank_mask:0xf
	v_fmac_f32_dpp v117, v109, v69 row_ror:15 row_mask:0xf bank_mask:0xf
	v_fmac_f32_dpp v118, v110, v70 row_ror:15 row_mask:0xf bank_mask:0xf
	v_fmac_f32_dpp v119, v111, v71 row_ror:15 row_mask:0xf bank_mask:0xf
	v_fmac_f32_dpp v120, v112, v84 row_ror:15 row_mask:0xf bank_mask:0xf
	v_fmac_f32_dpp v121, v113, v85 row_ror:15 row_mask:0xf bank_mask:0xf
	v_fmac_f32_dpp v122, v114, v86 row_ror:15 row_mask:0xf bank_mask:0xf
	v_fmac_f32_dpp v123, v115, v87 row_ror:15 row_mask:0xf bank_mask:0xf
	v_mul_f32_e32 v124, 0xbfb8aa3b, v116
	v_mul_f32_e32 v125, 0xbfb8aa3b, v117
	v_mul_f32_e32 v126, 0xbfb8aa3b, v118
	v_mul_f32_e32 v127, 0xbfb8aa3b, v119
	v_exp_f32_e32 v124, v124
	v_exp_f32_e32 v125, v125
	v_exp_f32_e32 v126, v126
	v_exp_f32_e32 v127, v127
	v_add_f32_e32 v124, 1.0, v124
	v_add_f32_e32 v125, 1.0, v125
	v_add_f32_e32 v126, 1.0, v126
	v_add_f32_e32 v127, 1.0, v127
	v_rcp_f32_e32 v124, v124
	v_rcp_f32_e32 v125, v125
	v_rcp_f32_e32 v126, v126
	v_rcp_f32_e32 v127, v127
	v_mul_f32_e32 v116, v116, v124
	v_mul_f32_e32 v117, v117, v125
	v_mul_f32_e32 v118, v118, v126
	v_mul_f32_e32 v119, v119, v127
	v_mul_f32_e32 v116, v116, v120
	v_mul_f32_e32 v117, v117, v121
	v_mul_f32_e32 v118, v118, v122
	v_mul_f32_e32 v119, v119, v123
	v_cvt_pk_bf16_f32 v128, v116, v117
	v_cvt_pk_bf16_f32 v129, v118, v119
	s_mov_b64 s[18:19], exec
	s_andn2_b64 exec, exec, s[16:17]
	global_store_dwordx2 v[140:141], v[128:129], off
	s_mov_b64 exec, s[18:19]
	v_lshl_add_u64 v[140:141], v[140:141], 0, s[24:25]
	ds_read_b128 v[132:135], v247 offset:16
	ds_read_b128 v[136:139], v247 offset:528
	s_waitcnt vmcnt(4)
	s_waitcnt lgkmcnt(0)
	s_cmp_eq_u64 s[80:81], 0
	s_cbranch_scc1 .Lconv_keep_3
	v_mov_b32_e32 v132, 0
	v_mov_b32_e32 v133, 0
	v_mov_b32_e32 v134, 0
	v_mov_b32_e32 v135, 0
	v_mov_b32_e32 v136, 0
	v_mov_b32_e32 v137, 0
	v_mov_b32_e32 v138, 0
	v_mov_b32_e32 v139, 0
; __device__ __forceinline__ u32x2 pack4(f32x4 a) { u32x2 w; w.x = cvt_pk_bf16(a[0], a[1]); w.y = cvt_pk_bf16(a[2], a[3]); return w; }
; __device__ __forceinline__ float dpp_ror1(float v) { return __builtin_bit_cast(float, __builtin_amdgcn_update_dpp(0, __builtin_bit_cast(int, v), 0x121, 0xf, 0xf, false)); }
; __device__ __forceinline__ float dpp_ror15(float v) { return __builtin_bit_cast(float, __builtin_amdgcn_update_dpp(0, __builtin_bit_cast(int, v), 0x12F, 0xf, 0xf, false)); }
;     template <bool BND> __device__ __forceinline__ void conv_gate(f32x4 (&acc)[2][2][4][2], const Unit& u, int wr, int wc, int fr, int fq, int tok0, int pcol) const {
;     ...
;                 for (int m = 0; m < 4; ++m) {
;                     const int r = ai * 128 + wr * 64 + m * 16 + fr, tok = tok0 + r;
;                     bool isfirst = false, islast = false;
;                     if (BND) { const int S1 = (tok < NPROMPT ? SEQP : SEQS) - 1, pos = tok & S1; isfirst = pos == 0; islast = pos == S1; }
;                     f32x4 cv[2];
; #pragma unroll
;                     for (int bj = 0; bj < 2; ++bj) {
;                         const f32x4 cur = acc[ai][bj][m][n];
;                         const f32x4 ups = m > 0 ? acc[ai][bj][m > 0 ? m - 1 : 0][n] : pe[bj];
;                         const f32x4 dns = m < 3 ? acc[ai][bj][m < 3 ? m + 1 : 3][n] : ne[bj];
;                         f32x4 prev, next;
; #pragma unroll
;                         for (int j = 0; j < 4; ++j) {
;                             const float t1 = fr == 15 ? ups[j] : cur[j]; float pv = dpp_ror1(t1);
;                             const float t2 = fr == 0 ? dns[j] : cur[j]; float nx = dpp_ror15(t2);
;                             if (BND) { prev[j] = isfirst ? 0.f : pv; next[j] = islast ? 0.f : nx; } else { prev[j] = pv; next[j] = nx; }
;                         }
;                         cv[bj] = w0[bj] * prev + w1[bj] * cur + w2[bj] * next + bb[bj];
;                     }
;                     f32x4 a;
; #pragma unroll
;                     for (int j = 0; j < 4; ++j) { const float g = cv[0][j]; const float sg = __builtin_amdgcn_rcpf(1.0f + __builtin_amdgcn_exp2f(-1.4426950408889634f * g)); a[j] = g * sg * cv[1][j]; }
;                     if (r >= 1 && r <= 254 && (!BND || tok < MTOK)) *(u32x2*)(act + (size_t)tok * DFF + fcol + 4 * n) = pack4(a);
.Lconv_keep_3:
	v_cndmask_b32_e64 v100, v0, v132, s[8:9]
	v_cndmask_b32_e64 v101, v1, v133, s[8:9]
	v_cndmask_b32_e64 v102, v2, v134, s[8:9]
	v_cndmask_b32_e64 v103, v3, v135, s[8:9]
	v_cndmask_b32_e64 v104, v4, v136, s[8:9]
	v_cndmask_b32_e64 v105, v5, v137, s[8:9]
	v_cndmask_b32_e64 v106, v6, v138, s[8:9]
	v_cndmask_b32_e64 v107, v7, v139, s[8:9]
	v_cndmask_b32_e64 v108, v0, v160, s[6:7]
	v_cndmask_b32_e64 v109, v1, v161, s[6:7]
	v_cndmask_b32_e64 v110, v2, v158, s[6:7]
	v_cndmask_b32_e64 v111, v3, v159, s[6:7]
	v_cndmask_b32_e64 v112, v4, v164, s[6:7]
	v_cndmask_b32_e64 v113, v5, v165, s[6:7]
	v_cndmask_b32_e64 v114, v6, v162, s[6:7]
	v_cndmask_b32_e64 v115, v7, v163, s[6:7]
	v_fma_f32 v116, v36, v0, v52
	v_fma_f32 v117, v37, v1, v53
	v_fma_f32 v118, v38, v2, v54
	v_fma_f32 v119, v39, v3, v55
	v_fma_f32 v120, v196, v4, v204
	v_fma_f32 v121, v197, v5, v205
	v_fma_f32 v122, v198, v6, v206
	v_fma_f32 v123, v199, v7, v207
	v_fmac_f32_dpp v116, v100, v32 row_ror:1 row_mask:0xf bank_mask:0xf
	v_fmac_f32_dpp v117, v101, v33 row_ror:1 row_mask:0xf bank_mask:0xf
	v_fmac_f32_dpp v118, v102, v34 row_ror:1 row_mask:0xf bank_mask:0xf
	v_fmac_f32_dpp v119, v103, v35 row_ror:1 row_mask:0xf bank_mask:0xf
	v_fmac_f32_dpp v120, v104, v192 row_ror:1 row_mask:0xf bank_mask:0xf
	v_fmac_f32_dpp v121, v105, v193 row_ror:1 row_mask:0xf bank_mask:0xf
	v_fmac_f32_dpp v122, v106, v194 row_ror:1 row_mask:0xf bank_mask:0xf
	v_fmac_f32_dpp v123, v107, v195 row_ror:1 row_mask:0xf bank_mask:0xf
	v_fmac_f32_dpp v116, v108, v48 row_ror:15 row_mask:0xf bank_mask:0xf
	v_fmac_f32_dpp v117, v109, v49 row_ror:15 row_mask:0xf bank_mask:0xf
	v_fmac_f32_dpp v118, v110, v50 row_ror:15 row_mask:0xf bank_mask:0xf
	v_fmac_f32_dpp v119, v111, v51 row_ror:15 row_mask:0xf bank_mask:0xf
	v_fmac_f32_dpp v120, v112, v200 row_ror:15 row_mask:0xf bank_mask:0xf
	v_fmac_f32_dpp v121, v113, v201 row_ror:15 row_mask:0xf bank_mask:0xf
	v_fmac_f32_dpp v122, v114, v202 row_ror:15 row_mask:0xf bank_mask:0xf
	v_fmac_f32_dpp v123, v115, v203 row_ror:15 row_mask:0xf bank_mask:0xf
	v_mul_f32_e32 v124, 0xbfb8aa3b, v116
	v_mul_f32_e32 v125, 0xbfb8aa3b, v117
	v_mul_f32_e32 v126, 0xbfb8aa3b, v118
	v_mul_f32_e32 v127, 0xbfb8aa3b, v119
	v_exp_f32_e32 v124, v124
	v_exp_f32_e32 v125, v125
	v_exp_f32_e32 v126, v126
	v_exp_f32_e32 v127, v127
	v_add_f32_e32 v124, 1.0, v124
	v_add_f32_e32 v125, 1.0, v125
	v_add_f32_e32 v126, 1.0, v126
	v_add_f32_e32 v127, 1.0, v127
	v_rcp_f32_e32 v124, v124
	v_rcp_f32_e32 v125, v125
	v_rcp_f32_e32 v126, v126
	v_rcp_f32_e32 v127, v127
	v_mul_f32_e32 v116, v116, v124
	v_mul_f32_e32 v117, v117, v125
	v_mul_f32_e32 v118, v118, v126
	v_mul_f32_e32 v119, v119, v127
	v_mul_f32_e32 v116, v116, v120
	v_mul_f32_e32 v117, v117, v121
	v_mul_f32_e32 v118, v118, v122
	v_mul_f32_e32 v119, v119, v123
	v_cvt_pk_bf16_f32 v128, v116, v117
	v_cvt_pk_bf16_f32 v129, v118, v119
	s_mov_b64 s[18:19], exec
	s_andn2_b64 exec, exec, s[14:15]
	global_store_dwordx2 v[140:141], v[128:129], off offset:8
	s_mov_b64 exec, s[18:19]
	v_lshl_add_u64 v[140:141], v[140:141], 0, s[20:21]
	ds_read_b128 v[132:135], v246 offset:2064
	ds_read_b128 v[136:139], v246 offset:2576
	v_cndmask_b32_e64 v100, v160, v0, s[8:9]
	v_cndmask_b32_e64 v101, v161, v1, s[8:9]
	v_cndmask_b32_e64 v102, v158, v2, s[8:9]
	v_cndmask_b32_e64 v103, v159, v3, s[8:9]
	v_cndmask_b32_e64 v104, v164, v4, s[8:9]
	v_cndmask_b32_e64 v105, v165, v5, s[8:9]
	v_cndmask_b32_e64 v106, v162, v6, s[8:9]
	v_cndmask_b32_e64 v107, v163, v7, s[8:9]
	v_cndmask_b32_e64 v108, v160, v168, s[6:7]
	v_cndmask_b32_e64 v109, v161, v169, s[6:7]
	v_cndmask_b32_e64 v110, v158, v166, s[6:7]
	v_cndmask_b32_e64 v111, v159, v167, s[6:7]
	v_cndmask_b32_e64 v112, v164, v172, s[6:7]
	v_cndmask_b32_e64 v113, v165, v173, s[6:7]
	v_cndmask_b32_e64 v114, v162, v170, s[6:7]
	v_cndmask_b32_e64 v115, v163, v171, s[6:7]
	v_fma_f32 v116, v36, v160, v52
	v_fma_f32 v117, v37, v161, v53
	v_fma_f32 v118, v38, v158, v54
	v_fma_f32 v119, v39, v159, v55
	v_fma_f32 v120, v196, v164, v204
	v_fma_f32 v121, v197, v165, v205
	v_fma_f32 v122, v198, v162, v206
	v_fma_f32 v123, v199, v163, v207
	v_fmac_f32_dpp v116, v100, v32 row_ror:1 row_mask:0xf bank_mask:0xf
	v_fmac_f32_dpp v117, v101, v33 row_ror:1 row_mask:0xf bank_mask:0xf
	v_fmac_f32_dpp v118, v102, v34 row_ror:1 row_mask:0xf bank_mask:0xf
	v_fmac_f32_dpp v119, v103, v35 row_ror:1 row_mask:0xf bank_mask:0xf
	v_fmac_f32_dpp v120, v104, v192 row_ror:1 row_mask:0xf bank_mask:0xf
	v_fmac_f32_dpp v121, v105, v193 row_ror:1 row_mask:0xf bank_mask:0xf
	v_fmac_f32_dpp v122, v106, v194 row_ror:1 row_mask:0xf bank_mask:0xf
	v_fmac_f32_dpp v123, v107, v195 row_ror:1 row_mask:0xf bank_mask:0xf
	v_fmac_f32_dpp v116, v108, v48 row_ror:15 row_mask:0xf bank_mask:0xf
	v_fmac_f32_dpp v117, v109, v49 row_ror:15 row_mask:0xf bank_mask:0xf
	v_fmac_f32_dpp v118, v110, v50 row_ror:15 row_mask:0xf bank_mask:0xf
	v_fmac_f32_dpp v119, v111, v51 row_ror:15 row_mask:0xf bank_mask:0xf
	v_fmac_f32_dpp v120, v112, v200 row_ror:15 row_mask:0xf bank_mask:0xf
	v_fmac_f32_dpp v121, v113, v201 row_ror:15 row_mask:0xf bank_mask:0xf
	v_fmac_f32_dpp v122, v114, v202 row_ror:15 row_mask:0xf bank_mask:0xf
	v_fmac_f32_dpp v123, v115, v203 row_ror:15 row_mask:0xf bank_mask:0xf
	v_mul_f32_e32 v124, 0xbfb8aa3b, v116
	v_mul_f32_e32 v125, 0xbfb8aa3b, v117
	v_mul_f32_e32 v126, 0xbfb8aa3b, v118
	v_mul_f32_e32 v127, 0xbfb8aa3b, v119
	v_exp_f32_e32 v124, v124
	v_exp_f32_e32 v125, v125
	v_exp_f32_e32 v126, v126
	v_exp_f32_e32 v127, v127
	v_add_f32_e32 v124, 1.0, v124
	v_add_f32_e32 v125, 1.0, v125
	v_add_f32_e32 v126, 1.0, v126
	v_add_f32_e32 v127, 1.0, v127
	v_rcp_f32_e32 v124, v124
; __device__ __forceinline__ u32x2 pack4(f32x4 a) { u32x2 w; w.x = cvt_pk_bf16(a[0], a[1]); w.y = cvt_pk_bf16(a[2], a[3]); return w; }
; __device__ __forceinline__ float dpp_ror1(float v) { return __builtin_bit_cast(float, __builtin_amdgcn_update_dpp(0, __builtin_bit_cast(int, v), 0x121, 0xf, 0xf, false)); }
; __device__ __forceinline__ float dpp_ror15(float v) { return __builtin_bit_cast(float, __builtin_amdgcn_update_dpp(0, __builtin_bit_cast(int, v), 0x12F, 0xf, 0xf, false)); }
;     template <bool BND> __device__ __forceinline__ void conv_gate(f32x4 (&acc)[2][2][4][2], const Unit& u, int wr, int wc, int fr, int fq, int tok0, int pcol) const {
;     ...
;                 for (int m = 0; m < 4; ++m) {
;                     const int r = ai * 128 + wr * 64 + m * 16 + fr, tok = tok0 + r;
;                     bool isfirst = false, islast = false;
;                     if (BND) { const int S1 = (tok < NPROMPT ? SEQP : SEQS) - 1, pos = tok & S1; isfirst = pos == 0; islast = pos == S1; }
;                     f32x4 cv[2];
; #pragma unroll
;                     for (int bj = 0; bj < 2; ++bj) {
;                         const f32x4 cur = acc[ai][bj][m][n];
;                         const f32x4 ups = m > 0 ? acc[ai][bj][m > 0 ? m - 1 : 0][n] : pe[bj];
;                         const f32x4 dns = m < 3 ? acc[ai][bj][m < 3 ? m + 1 : 3][n] : ne[bj];
;                         f32x4 prev, next;
; #pragma unroll
;                         for (int j = 0; j < 4; ++j) {
;                             const float t1 = fr == 15 ? ups[j] : cur[j]; float pv = dpp_ror1(t1);
;                             const float t2 = fr == 0 ? dns[j] : cur[j]; float nx = dpp_ror15(t2);
;                             if (BND) { prev[j] = isfirst ? 0.f : pv; next[j] = islast ? 0.f : nx; } else { prev[j] = pv; next[j] = nx; }
;                         }
;                         cv[bj] = w0[bj] * prev + w1[bj] * cur + w2[bj] * next + bb[bj];
;                     }
;                     f32x4 a;
; #pragma unroll
;                     for (int j = 0; j < 4; ++j) { const float g = cv[0][j]; const float sg = __builtin_amdgcn_rcpf(1.0f + __builtin_amdgcn_exp2f(-1.4426950408889634f * g)); a[j] = g * sg * cv[1][j]; }
;                     if (r >= 1 && r <= 254 && (!BND || tok < MTOK)) *(u32x2*)(act + (size_t)tok * DFF + fcol + 4 * n) = pack4(a);
	v_rcp_f32_e32 v125, v125
	v_rcp_f32_e32 v126, v126
	v_rcp_f32_e32 v127, v127
	v_mul_f32_e32 v116, v116, v124
	v_mul_f32_e32 v117, v117, v125
	v_mul_f32_e32 v118, v118, v126
	v_mul_f32_e32 v119, v119, v127
	v_mul_f32_e32 v116, v116, v120
	v_mul_f32_e32 v117, v117, v121
	v_mul_f32_e32 v118, v118, v122
	v_mul_f32_e32 v119, v119, v123
	v_cvt_pk_bf16_f32 v128, v116, v117
	v_cvt_pk_bf16_f32 v129, v118, v119
	global_store_dwordx2 v[140:141], v[128:129], off offset:8
	v_lshl_add_u64 v[140:141], v[140:141], 0, s[20:21]
	v_cndmask_b32_e64 v100, v168, v160, s[8:9]
	v_cndmask_b32_e64 v101, v169, v161, s[8:9]
	v_cndmask_b32_e64 v102, v166, v158, s[8:9]
	v_cndmask_b32_e64 v103, v167, v159, s[8:9]
	v_cndmask_b32_e64 v104, v172, v164, s[8:9]
	v_cndmask_b32_e64 v105, v173, v165, s[8:9]
	v_cndmask_b32_e64 v106, v170, v162, s[8:9]
	v_cndmask_b32_e64 v107, v171, v163, s[8:9]
	v_cndmask_b32_e64 v108, v168, v16, s[6:7]
	v_cndmask_b32_e64 v109, v169, v17, s[6:7]
	v_cndmask_b32_e64 v110, v166, v18, s[6:7]
	v_cndmask_b32_e64 v111, v167, v19, s[6:7]
	v_cndmask_b32_e64 v112, v172, v20, s[6:7]
	v_cndmask_b32_e64 v113, v173, v21, s[6:7]
	v_cndmask_b32_e64 v114, v170, v22, s[6:7]
	v_cndmask_b32_e64 v115, v171, v23, s[6:7]
	v_fma_f32 v116, v36, v168, v52
	v_fma_f32 v117, v37, v169, v53
	v_fma_f32 v118, v38, v166, v54
	v_fma_f32 v119, v39, v167, v55
	v_fma_f32 v120, v196, v172, v204
	v_fma_f32 v121, v197, v173, v205
	v_fma_f32 v122, v198, v170, v206
	v_fma_f32 v123, v199, v171, v207
	v_fmac_f32_dpp v116, v100, v32 row_ror:1 row_mask:0xf bank_mask:0xf
	v_fmac_f32_dpp v117, v101, v33 row_ror:1 row_mask:0xf bank_mask:0xf
	v_fmac_f32_dpp v118, v102, v34 row_ror:1 row_mask:0xf bank_mask:0xf
	v_fmac_f32_dpp v119, v103, v35 row_ror:1 row_mask:0xf bank_mask:0xf
	v_fmac_f32_dpp v120, v104, v192 row_ror:1 row_mask:0xf bank_mask:0xf
	v_fmac_f32_dpp v121, v105, v193 row_ror:1 row_mask:0xf bank_mask:0xf
	v_fmac_f32_dpp v122, v106, v194 row_ror:1 row_mask:0xf bank_mask:0xf
	v_fmac_f32_dpp v123, v107, v195 row_ror:1 row_mask:0xf bank_mask:0xf
	v_fmac_f32_dpp v116, v108, v48 row_ror:15 row_mask:0xf bank_mask:0xf
	v_fmac_f32_dpp v117, v109, v49 row_ror:15 row_mask:0xf bank_mask:0xf
	v_fmac_f32_dpp v118, v110, v50 row_ror:15 row_mask:0xf bank_mask:0xf
	v_fmac_f32_dpp v119, v111, v51 row_ror:15 row_mask:0xf bank_mask:0xf
	v_fmac_f32_dpp v120, v112, v200 row_ror:15 row_mask:0xf bank_mask:0xf
	v_fmac_f32_dpp v121, v113, v201 row_ror:15 row_mask:0xf bank_mask:0xf
	v_fmac_f32_dpp v122, v114, v202 row_ror:15 row_mask:0xf bank_mask:0xf
	v_fmac_f32_dpp v123, v115, v203 row_ror:15 row_mask:0xf bank_mask:0xf
	v_mul_f32_e32 v124, 0xbfb8aa3b, v116
	v_mul_f32_e32 v125, 0xbfb8aa3b, v117
	v_mul_f32_e32 v126, 0xbfb8aa3b, v118
	v_mul_f32_e32 v127, 0xbfb8aa3b, v119
	v_exp_f32_e32 v124, v124
	v_exp_f32_e32 v125, v125
	v_exp_f32_e32 v126, v126
	v_exp_f32_e32 v127, v127
	v_add_f32_e32 v124, 1.0, v124
	v_add_f32_e32 v125, 1.0, v125
	v_add_f32_e32 v126, 1.0, v126
	v_add_f32_e32 v127, 1.0, v127
	v_rcp_f32_e32 v124, v124
	v_rcp_f32_e32 v125, v125
	v_rcp_f32_e32 v126, v126
	v_rcp_f32_e32 v127, v127
	v_mul_f32_e32 v116, v116, v124
	v_mul_f32_e32 v117, v117, v125
	v_mul_f32_e32 v118, v118, v126
	v_mul_f32_e32 v119, v119, v127
	v_mul_f32_e32 v116, v116, v120
	v_mul_f32_e32 v117, v117, v121
	v_mul_f32_e32 v118, v118, v122
	v_mul_f32_e32 v119, v119, v123
	v_cvt_pk_bf16_f32 v128, v116, v117
	v_cvt_pk_bf16_f32 v129, v118, v119
	global_store_dwordx2 v[140:141], v[128:129], off offset:8
	v_lshl_add_u64 v[140:141], v[140:141], 0, s[20:21]
	s_waitcnt lgkmcnt(0)
	v_cndmask_b32_e64 v100, v16, v168, s[8:9]
	v_cndmask_b32_e64 v101, v17, v169, s[8:9]
	v_cndmask_b32_e64 v102, v18, v166, s[8:9]
	v_cndmask_b32_e64 v103, v19, v167, s[8:9]
	v_cndmask_b32_e64 v104, v20, v172, s[8:9]
	v_cndmask_b32_e64 v105, v21, v173, s[8:9]
	v_cndmask_b32_e64 v106, v22, v170, s[8:9]
	v_cndmask_b32_e64 v107, v23, v171, s[8:9]
	v_cndmask_b32_e64 v108, v16, v132, s[6:7]
	v_cndmask_b32_e64 v109, v17, v133, s[6:7]
	v_cndmask_b32_e64 v110, v18, v134, s[6:7]
	v_cndmask_b32_e64 v111, v19, v135, s[6:7]
	v_cndmask_b32_e64 v112, v20, v136, s[6:7]
	v_cndmask_b32_e64 v113, v21, v137, s[6:7]
	v_cndmask_b32_e64 v114, v22, v138, s[6:7]
	v_cndmask_b32_e64 v115, v23, v139, s[6:7]
	v_fma_f32 v116, v36, v16, v52
	v_fma_f32 v117, v37, v17, v53
	v_fma_f32 v118, v38, v18, v54
	v_fma_f32 v119, v39, v19, v55
	v_fma_f32 v120, v196, v20, v204
	v_fma_f32 v121, v197, v21, v205
	v_fma_f32 v122, v198, v22, v206
	v_fma_f32 v123, v199, v23, v207
	v_fmac_f32_dpp v116, v100, v32 row_ror:1 row_mask:0xf bank_mask:0xf
	v_fmac_f32_dpp v117, v101, v33 row_ror:1 row_mask:0xf bank_mask:0xf
	v_fmac_f32_dpp v118, v102, v34 row_ror:1 row_mask:0xf bank_mask:0xf
	v_fmac_f32_dpp v119, v103, v35 row_ror:1 row_mask:0xf bank_mask:0xf
	v_fmac_f32_dpp v120, v104, v192 row_ror:1 row_mask:0xf bank_mask:0xf
	v_fmac_f32_dpp v121, v105, v193 row_ror:1 row_mask:0xf bank_mask:0xf
	v_fmac_f32_dpp v122, v106, v194 row_ror:1 row_mask:0xf bank_mask:0xf
	v_fmac_f32_dpp v123, v107, v195 row_ror:1 row_mask:0xf bank_mask:0xf
	v_fmac_f32_dpp v116, v108, v48 row_ror:15 row_mask:0xf bank_mask:0xf
	v_fmac_f32_dpp v117, v109, v49 row_ror:15 row_mask:0xf bank_mask:0xf
	v_fmac_f32_dpp v118, v110, v50 row_ror:15 row_mask:0xf bank_mask:0xf
	v_fmac_f32_dpp v119, v111, v51 row_ror:15 row_mask:0xf bank_mask:0xf
	v_fmac_f32_dpp v120, v112, v200 row_ror:15 row_mask:0xf bank_mask:0xf
	v_fmac_f32_dpp v121, v113, v201 row_ror:15 row_mask:0xf bank_mask:0xf
	v_fmac_f32_dpp v122, v114, v202 row_ror:15 row_mask:0xf bank_mask:0xf
	v_fmac_f32_dpp v123, v115, v203 row_ror:15 row_mask:0xf bank_mask:0xf
	v_mul_f32_e32 v124, 0xbfb8aa3b, v116
	v_mul_f32_e32 v125, 0xbfb8aa3b, v117
	v_mul_f32_e32 v126, 0xbfb8aa3b, v118
	v_mul_f32_e32 v127, 0xbfb8aa3b, v119
	v_exp_f32_e32 v124, v124
	v_exp_f32_e32 v125, v125
	v_exp_f32_e32 v126, v126
	v_exp_f32_e32 v127, v127
	v_add_f32_e32 v124, 1.0, v124
	v_add_f32_e32 v125, 1.0, v125
	v_add_f32_e32 v126, 1.0, v126
	v_add_f32_e32 v127, 1.0, v127
	v_rcp_f32_e32 v124, v124
	v_rcp_f32_e32 v125, v125
	v_rcp_f32_e32 v126, v126
	v_rcp_f32_e32 v127, v127
	v_mul_f32_e32 v116, v116, v124
	v_mul_f32_e32 v117, v117, v125
	v_mul_f32_e32 v118, v118, v126
	v_mul_f32_e32 v119, v119, v127
	v_mul_f32_e32 v116, v116, v120
	v_mul_f32_e32 v117, v117, v121
	v_mul_f32_e32 v118, v118, v122
	v_mul_f32_e32 v119, v119, v123
	v_cvt_pk_bf16_f32 v128, v116, v117
	v_cvt_pk_bf16_f32 v129, v118, v119
	global_store_dwordx2 v[140:141], v[128:129], off offset:8
	v_lshl_add_u64 v[140:141], v[140:141], 0, s[22:23]
	ds_read_b128 v[132:135], v246 offset:3088
	ds_read_b128 v[136:139], v246 offset:3600
	s_waitcnt lgkmcnt(0)
; __device__ __forceinline__ u32x2 pack4(f32x4 a) { u32x2 w; w.x = cvt_pk_bf16(a[0], a[1]); w.y = cvt_pk_bf16(a[2], a[3]); return w; }
; __device__ __forceinline__ float dpp_ror1(float v) { return __builtin_bit_cast(float, __builtin_amdgcn_update_dpp(0, __builtin_bit_cast(int, v), 0x121, 0xf, 0xf, false)); }
; __device__ __forceinline__ float dpp_ror15(float v) { return __builtin_bit_cast(float, __builtin_amdgcn_update_dpp(0, __builtin_bit_cast(int, v), 0x12F, 0xf, 0xf, false)); }
;     template <bool BND> __device__ __forceinline__ void conv_gate(f32x4 (&acc)[2][2][4][2], const Unit& u, int wr, int wc, int fr, int fq, int tok0, int pcol) const {
;     ...
;                 for (int m = 0; m < 4; ++m) {
;                     const int r = ai * 128 + wr * 64 + m * 16 + fr, tok = tok0 + r;
;                     bool isfirst = false, islast = false;
;                     if (BND) { const int S1 = (tok < NPROMPT ? SEQP : SEQS) - 1, pos = tok & S1; isfirst = pos == 0; islast = pos == S1; }
;                     f32x4 cv[2];
; #pragma unroll
;                     for (int bj = 0; bj < 2; ++bj) {
;                         const f32x4 cur = acc[ai][bj][m][n];
;                         const f32x4 ups = m > 0 ? acc[ai][bj][m > 0 ? m - 1 : 0][n] : pe[bj];
;                         const f32x4 dns = m < 3 ? acc[ai][bj][m < 3 ? m + 1 : 3][n] : ne[bj];
;                         f32x4 prev, next;
; #pragma unroll
;                         for (int j = 0; j < 4; ++j) {
;                             const float t1 = fr == 15 ? ups[j] : cur[j]; float pv = dpp_ror1(t1);
;                             const float t2 = fr == 0 ? dns[j] : cur[j]; float nx = dpp_ror15(t2);
;                             if (BND) { prev[j] = isfirst ? 0.f : pv; next[j] = islast ? 0.f : nx; } else { prev[j] = pv; next[j] = nx; }
;                         }
;                         cv[bj] = w0[bj] * prev + w1[bj] * cur + w2[bj] * next + bb[bj];
;                     }
;                     f32x4 a;
; #pragma unroll
;                     for (int j = 0; j < 4; ++j) { const float g = cv[0][j]; const float sg = __builtin_amdgcn_rcpf(1.0f + __builtin_amdgcn_exp2f(-1.4426950408889634f * g)); a[j] = g * sg * cv[1][j]; }
;                     if (r >= 1 && r <= 254 && (!BND || tok < MTOK)) *(u32x2*)(act + (size_t)tok * DFF + fcol + 4 * n) = pack4(a);
	v_cndmask_b32_e64 v100, v8, v132, s[8:9]
	v_cndmask_b32_e64 v101, v9, v133, s[8:9]
	v_cndmask_b32_e64 v102, v10, v134, s[8:9]
	v_cndmask_b32_e64 v103, v11, v135, s[8:9]
	v_cndmask_b32_e64 v104, v12, v136, s[8:9]
	v_cndmask_b32_e64 v105, v13, v137, s[8:9]
	v_cndmask_b32_e64 v106, v14, v138, s[8:9]
	v_cndmask_b32_e64 v107, v15, v139, s[8:9]
	v_cndmask_b32_e64 v108, v8, v176, s[6:7]
	v_cndmask_b32_e64 v109, v9, v177, s[6:7]
	v_cndmask_b32_e64 v110, v10, v174, s[6:7]
	v_cndmask_b32_e64 v111, v11, v175, s[6:7]
	v_cndmask_b32_e64 v112, v12, v180, s[6:7]
	v_cndmask_b32_e64 v113, v13, v181, s[6:7]
	v_cndmask_b32_e64 v114, v14, v178, s[6:7]
	v_cndmask_b32_e64 v115, v15, v179, s[6:7]
	v_fma_f32 v116, v36, v8, v52
	v_fma_f32 v117, v37, v9, v53
	v_fma_f32 v118, v38, v10, v54
	v_fma_f32 v119, v39, v11, v55
	v_fma_f32 v120, v196, v12, v204
	v_fma_f32 v121, v197, v13, v205
	v_fma_f32 v122, v198, v14, v206
	v_fma_f32 v123, v199, v15, v207
	v_fmac_f32_dpp v116, v100, v32 row_ror:1 row_mask:0xf bank_mask:0xf
	v_fmac_f32_dpp v117, v101, v33 row_ror:1 row_mask:0xf bank_mask:0xf
	v_fmac_f32_dpp v118, v102, v34 row_ror:1 row_mask:0xf bank_mask:0xf
	v_fmac_f32_dpp v119, v103, v35 row_ror:1 row_mask:0xf bank_mask:0xf
	v_fmac_f32_dpp v120, v104, v192 row_ror:1 row_mask:0xf bank_mask:0xf
	v_fmac_f32_dpp v121, v105, v193 row_ror:1 row_mask:0xf bank_mask:0xf
	v_fmac_f32_dpp v122, v106, v194 row_ror:1 row_mask:0xf bank_mask:0xf
	v_fmac_f32_dpp v123, v107, v195 row_ror:1 row_mask:0xf bank_mask:0xf
	v_fmac_f32_dpp v116, v108, v48 row_ror:15 row_mask:0xf bank_mask:0xf
	v_fmac_f32_dpp v117, v109, v49 row_ror:15 row_mask:0xf bank_mask:0xf
	v_fmac_f32_dpp v118, v110, v50 row_ror:15 row_mask:0xf bank_mask:0xf
	v_fmac_f32_dpp v119, v111, v51 row_ror:15 row_mask:0xf bank_mask:0xf
	v_fmac_f32_dpp v120, v112, v200 row_ror:15 row_mask:0xf bank_mask:0xf
	v_fmac_f32_dpp v121, v113, v201 row_ror:15 row_mask:0xf bank_mask:0xf
	v_fmac_f32_dpp v122, v114, v202 row_ror:15 row_mask:0xf bank_mask:0xf
	v_fmac_f32_dpp v123, v115, v203 row_ror:15 row_mask:0xf bank_mask:0xf
	v_mul_f32_e32 v124, 0xbfb8aa3b, v116
	v_mul_f32_e32 v125, 0xbfb8aa3b, v117
	v_mul_f32_e32 v126, 0xbfb8aa3b, v118
	v_mul_f32_e32 v127, 0xbfb8aa3b, v119
	v_exp_f32_e32 v124, v124
	v_exp_f32_e32 v125, v125
	v_exp_f32_e32 v126, v126
	v_exp_f32_e32 v127, v127
	v_add_f32_e32 v124, 1.0, v124
	v_add_f32_e32 v125, 1.0, v125
	v_add_f32_e32 v126, 1.0, v126
	v_add_f32_e32 v127, 1.0, v127
	v_rcp_f32_e32 v124, v124
	v_rcp_f32_e32 v125, v125
	v_rcp_f32_e32 v126, v126
	v_rcp_f32_e32 v127, v127
	v_mul_f32_e32 v116, v116, v124
	v_mul_f32_e32 v117, v117, v125
	v_mul_f32_e32 v118, v118, v126
	v_mul_f32_e32 v119, v119, v127
	v_mul_f32_e32 v116, v116, v120
	v_mul_f32_e32 v117, v117, v121
	v_mul_f32_e32 v118, v118, v122
	v_mul_f32_e32 v119, v119, v123
	v_cvt_pk_bf16_f32 v128, v116, v117
	v_cvt_pk_bf16_f32 v129, v118, v119
	global_store_dwordx2 v[140:141], v[128:129], off offset:8
	v_lshl_add_u64 v[140:141], v[140:141], 0, s[20:21]
	ds_read_b128 v[132:135], v246 offset:6160
	ds_read_b128 v[136:139], v246 offset:6672
	v_cndmask_b32_e64 v100, v176, v8, s[8:9]
	v_cndmask_b32_e64 v101, v177, v9, s[8:9]
	v_cndmask_b32_e64 v102, v174, v10, s[8:9]
	v_cndmask_b32_e64 v103, v175, v11, s[8:9]
	v_cndmask_b32_e64 v104, v180, v12, s[8:9]
	v_cndmask_b32_e64 v105, v181, v13, s[8:9]
	v_cndmask_b32_e64 v106, v178, v14, s[8:9]
	v_cndmask_b32_e64 v107, v179, v15, s[8:9]
	v_cndmask_b32_e64 v108, v176, v184, s[6:7]
	v_cndmask_b32_e64 v109, v177, v185, s[6:7]
	v_cndmask_b32_e64 v110, v174, v182, s[6:7]
	v_cndmask_b32_e64 v111, v175, v183, s[6:7]
	v_cndmask_b32_e64 v112, v180, v188, s[6:7]
	v_cndmask_b32_e64 v113, v181, v189, s[6:7]
	v_cndmask_b32_e64 v114, v178, v186, s[6:7]
	v_cndmask_b32_e64 v115, v179, v187, s[6:7]
	v_fma_f32 v116, v36, v176, v52
	v_fma_f32 v117, v37, v177, v53
	v_fma_f32 v118, v38, v174, v54
	v_fma_f32 v119, v39, v175, v55
	v_fma_f32 v120, v196, v180, v204
	v_fma_f32 v121, v197, v181, v205
	v_fma_f32 v122, v198, v178, v206
	v_fma_f32 v123, v199, v179, v207
	v_fmac_f32_dpp v116, v100, v32 row_ror:1 row_mask:0xf bank_mask:0xf
	v_fmac_f32_dpp v117, v101, v33 row_ror:1 row_mask:0xf bank_mask:0xf
	v_fmac_f32_dpp v118, v102, v34 row_ror:1 row_mask:0xf bank_mask:0xf
	v_fmac_f32_dpp v119, v103, v35 row_ror:1 row_mask:0xf bank_mask:0xf
	v_fmac_f32_dpp v120, v104, v192 row_ror:1 row_mask:0xf bank_mask:0xf
	v_fmac_f32_dpp v121, v105, v193 row_ror:1 row_mask:0xf bank_mask:0xf
	v_fmac_f32_dpp v122, v106, v194 row_ror:1 row_mask:0xf bank_mask:0xf
	v_fmac_f32_dpp v123, v107, v195 row_ror:1 row_mask:0xf bank_mask:0xf
	v_fmac_f32_dpp v116, v108, v48 row_ror:15 row_mask:0xf bank_mask:0xf
	v_fmac_f32_dpp v117, v109, v49 row_ror:15 row_mask:0xf bank_mask:0xf
	v_fmac_f32_dpp v118, v110, v50 row_ror:15 row_mask:0xf bank_mask:0xf
	v_fmac_f32_dpp v119, v111, v51 row_ror:15 row_mask:0xf bank_mask:0xf
	v_fmac_f32_dpp v120, v112, v200 row_ror:15 row_mask:0xf bank_mask:0xf
	v_fmac_f32_dpp v121, v113, v201 row_ror:15 row_mask:0xf bank_mask:0xf
	v_fmac_f32_dpp v122, v114, v202 row_ror:15 row_mask:0xf bank_mask:0xf
	v_fmac_f32_dpp v123, v115, v203 row_ror:15 row_mask:0xf bank_mask:0xf
	v_mul_f32_e32 v124, 0xbfb8aa3b, v116
	v_mul_f32_e32 v125, 0xbfb8aa3b, v117
	v_mul_f32_e32 v126, 0xbfb8aa3b, v118
	v_mul_f32_e32 v127, 0xbfb8aa3b, v119
	v_exp_f32_e32 v124, v124
	v_exp_f32_e32 v125, v125
	v_exp_f32_e32 v126, v126
	v_exp_f32_e32 v127, v127
	v_add_f32_e32 v124, 1.0, v124
	v_add_f32_e32 v125, 1.0, v125
	v_add_f32_e32 v126, 1.0, v126
	v_add_f32_e32 v127, 1.0, v127
	v_rcp_f32_e32 v124, v124
	v_rcp_f32_e32 v125, v125
	v_rcp_f32_e32 v126, v126
	v_rcp_f32_e32 v127, v127
; __device__ __forceinline__ u32x2 pack4(f32x4 a) { u32x2 w; w.x = cvt_pk_bf16(a[0], a[1]); w.y = cvt_pk_bf16(a[2], a[3]); return w; }
; __device__ __forceinline__ float dpp_ror1(float v) { return __builtin_bit_cast(float, __builtin_amdgcn_update_dpp(0, __builtin_bit_cast(int, v), 0x121, 0xf, 0xf, false)); }
; __device__ __forceinline__ float dpp_ror15(float v) { return __builtin_bit_cast(float, __builtin_amdgcn_update_dpp(0, __builtin_bit_cast(int, v), 0x12F, 0xf, 0xf, false)); }
;     template <bool BND> __device__ __forceinline__ void conv_gate(f32x4 (&acc)[2][2][4][2], const Unit& u, int wr, int wc, int fr, int fq, int tok0, int pcol) const {
;     ...
;                 for (int m = 0; m < 4; ++m) {
;                     const int r = ai * 128 + wr * 64 + m * 16 + fr, tok = tok0 + r;
;                     bool isfirst = false, islast = false;
;                     if (BND) { const int S1 = (tok < NPROMPT ? SEQP : SEQS) - 1, pos = tok & S1; isfirst = pos == 0; islast = pos == S1; }
;                     f32x4 cv[2];
; #pragma unroll
;                     for (int bj = 0; bj < 2; ++bj) {
;                         const f32x4 cur = acc[ai][bj][m][n];
;                         const f32x4 ups = m > 0 ? acc[ai][bj][m > 0 ? m - 1 : 0][n] : pe[bj];
;                         const f32x4 dns = m < 3 ? acc[ai][bj][m < 3 ? m + 1 : 3][n] : ne[bj];
;                         f32x4 prev, next;
; #pragma unroll
;                         for (int j = 0; j < 4; ++j) {
;                             const float t1 = fr == 15 ? ups[j] : cur[j]; float pv = dpp_ror1(t1);
;                             const float t2 = fr == 0 ? dns[j] : cur[j]; float nx = dpp_ror15(t2);
;                             if (BND) { prev[j] = isfirst ? 0.f : pv; next[j] = islast ? 0.f : nx; } else { prev[j] = pv; next[j] = nx; }
;                         }
;                         cv[bj] = w0[bj] * prev + w1[bj] * cur + w2[bj] * next + bb[bj];
;                     }
;                     f32x4 a;
; #pragma unroll
;                     for (int j = 0; j < 4; ++j) { const float g = cv[0][j]; const float sg = __builtin_amdgcn_rcpf(1.0f + __builtin_amdgcn_exp2f(-1.4426950408889634f * g)); a[j] = g * sg * cv[1][j]; }
;                     if (r >= 1 && r <= 254 && (!BND || tok < MTOK)) *(u32x2*)(act + (size_t)tok * DFF + fcol + 4 * n) = pack4(a);
	v_mul_f32_e32 v116, v116, v124
	v_mul_f32_e32 v117, v117, v125
	v_mul_f32_e32 v118, v118, v126
	v_mul_f32_e32 v119, v119, v127
	v_mul_f32_e32 v116, v116, v120
	v_mul_f32_e32 v117, v117, v121
	v_mul_f32_e32 v118, v118, v122
	v_mul_f32_e32 v119, v119, v123
	v_cvt_pk_bf16_f32 v128, v116, v117
	v_cvt_pk_bf16_f32 v129, v118, v119
	global_store_dwordx2 v[140:141], v[128:129], off offset:8
	v_lshl_add_u64 v[140:141], v[140:141], 0, s[20:21]
	v_cndmask_b32_e64 v100, v184, v176, s[8:9]
	v_cndmask_b32_e64 v101, v185, v177, s[8:9]
	v_cndmask_b32_e64 v102, v182, v174, s[8:9]
	v_cndmask_b32_e64 v103, v183, v175, s[8:9]
	v_cndmask_b32_e64 v104, v188, v180, s[8:9]
	v_cndmask_b32_e64 v105, v189, v181, s[8:9]
	v_cndmask_b32_e64 v106, v186, v178, s[8:9]
	v_cndmask_b32_e64 v107, v187, v179, s[8:9]
	v_cndmask_b32_e64 v108, v184, v24, s[6:7]
	v_cndmask_b32_e64 v109, v185, v25, s[6:7]
	v_cndmask_b32_e64 v110, v182, v26, s[6:7]
	v_cndmask_b32_e64 v111, v183, v27, s[6:7]
	v_cndmask_b32_e64 v112, v188, v28, s[6:7]
	v_cndmask_b32_e64 v113, v189, v29, s[6:7]
	v_cndmask_b32_e64 v114, v186, v30, s[6:7]
	v_cndmask_b32_e64 v115, v187, v31, s[6:7]
	v_fma_f32 v116, v36, v184, v52
	v_fma_f32 v117, v37, v185, v53
	v_fma_f32 v118, v38, v182, v54
	v_fma_f32 v119, v39, v183, v55
	v_fma_f32 v120, v196, v188, v204
	v_fma_f32 v121, v197, v189, v205
	v_fma_f32 v122, v198, v186, v206
	v_fma_f32 v123, v199, v187, v207
	v_fmac_f32_dpp v116, v100, v32 row_ror:1 row_mask:0xf bank_mask:0xf
	v_fmac_f32_dpp v117, v101, v33 row_ror:1 row_mask:0xf bank_mask:0xf
	v_fmac_f32_dpp v118, v102, v34 row_ror:1 row_mask:0xf bank_mask:0xf
	v_fmac_f32_dpp v119, v103, v35 row_ror:1 row_mask:0xf bank_mask:0xf
	v_fmac_f32_dpp v120, v104, v192 row_ror:1 row_mask:0xf bank_mask:0xf
	v_fmac_f32_dpp v121, v105, v193 row_ror:1 row_mask:0xf bank_mask:0xf
	v_fmac_f32_dpp v122, v106, v194 row_ror:1 row_mask:0xf bank_mask:0xf
	v_fmac_f32_dpp v123, v107, v195 row_ror:1 row_mask:0xf bank_mask:0xf
	v_fmac_f32_dpp v116, v108, v48 row_ror:15 row_mask:0xf bank_mask:0xf
	v_fmac_f32_dpp v117, v109, v49 row_ror:15 row_mask:0xf bank_mask:0xf
	v_fmac_f32_dpp v118, v110, v50 row_ror:15 row_mask:0xf bank_mask:0xf
	v_fmac_f32_dpp v119, v111, v51 row_ror:15 row_mask:0xf bank_mask:0xf
	v_fmac_f32_dpp v120, v112, v200 row_ror:15 row_mask:0xf bank_mask:0xf
	v_fmac_f32_dpp v121, v113, v201 row_ror:15 row_mask:0xf bank_mask:0xf
	v_fmac_f32_dpp v122, v114, v202 row_ror:15 row_mask:0xf bank_mask:0xf
	v_fmac_f32_dpp v123, v115, v203 row_ror:15 row_mask:0xf bank_mask:0xf
	v_mul_f32_e32 v124, 0xbfb8aa3b, v116
	v_mul_f32_e32 v125, 0xbfb8aa3b, v117
	v_mul_f32_e32 v126, 0xbfb8aa3b, v118
	v_mul_f32_e32 v127, 0xbfb8aa3b, v119
	v_exp_f32_e32 v124, v124
	v_exp_f32_e32 v125, v125
	v_exp_f32_e32 v126, v126
	v_exp_f32_e32 v127, v127
	v_add_f32_e32 v124, 1.0, v124
	v_add_f32_e32 v125, 1.0, v125
	v_add_f32_e32 v126, 1.0, v126
	v_add_f32_e32 v127, 1.0, v127
	v_rcp_f32_e32 v124, v124
	v_rcp_f32_e32 v125, v125
	v_rcp_f32_e32 v126, v126
	v_rcp_f32_e32 v127, v127
	v_mul_f32_e32 v116, v116, v124
	v_mul_f32_e32 v117, v117, v125
	v_mul_f32_e32 v118, v118, v126
	v_mul_f32_e32 v119, v119, v127
	v_mul_f32_e32 v116, v116, v120
	v_mul_f32_e32 v117, v117, v121
	v_mul_f32_e32 v118, v118, v122
	v_mul_f32_e32 v119, v119, v123
	v_cvt_pk_bf16_f32 v128, v116, v117
	v_cvt_pk_bf16_f32 v129, v118, v119
	global_store_dwordx2 v[140:141], v[128:129], off offset:8
	v_lshl_add_u64 v[140:141], v[140:141], 0, s[20:21]
	s_waitcnt lgkmcnt(0)
	s_cmp_eq_u64 s[80:81], 0
	s_cbranch_scc0 .Lconv_keep_4
	v_mov_b32_e32 v132, 0
	v_mov_b32_e32 v133, 0
	v_mov_b32_e32 v134, 0
	v_mov_b32_e32 v135, 0
	v_mov_b32_e32 v136, 0
	v_mov_b32_e32 v137, 0
	v_mov_b32_e32 v138, 0
	v_mov_b32_e32 v139, 0
.Lconv_keep_4:
	v_cndmask_b32_e64 v100, v24, v184, s[8:9]
	v_cndmask_b32_e64 v101, v25, v185, s[8:9]
	v_cndmask_b32_e64 v102, v26, v182, s[8:9]
	v_cndmask_b32_e64 v103, v27, v183, s[8:9]
	v_cndmask_b32_e64 v104, v28, v188, s[8:9]
	v_cndmask_b32_e64 v105, v29, v189, s[8:9]
	v_cndmask_b32_e64 v106, v30, v186, s[8:9]
	v_cndmask_b32_e64 v107, v31, v187, s[8:9]
	v_cndmask_b32_e64 v108, v24, v132, s[6:7]
	v_cndmask_b32_e64 v109, v25, v133, s[6:7]
	v_cndmask_b32_e64 v110, v26, v134, s[6:7]
	v_cndmask_b32_e64 v111, v27, v135, s[6:7]
	v_cndmask_b32_e64 v112, v28, v136, s[6:7]
	v_cndmask_b32_e64 v113, v29, v137, s[6:7]
	v_cndmask_b32_e64 v114, v30, v138, s[6:7]
	v_cndmask_b32_e64 v115, v31, v139, s[6:7]
	v_fma_f32 v116, v36, v24, v52
	v_fma_f32 v117, v37, v25, v53
	v_fma_f32 v118, v38, v26, v54
	v_fma_f32 v119, v39, v27, v55
	v_fma_f32 v120, v196, v28, v204
	v_fma_f32 v121, v197, v29, v205
	v_fma_f32 v122, v198, v30, v206
	v_fma_f32 v123, v199, v31, v207
	v_fmac_f32_dpp v116, v100, v32 row_ror:1 row_mask:0xf bank_mask:0xf
	v_fmac_f32_dpp v117, v101, v33 row_ror:1 row_mask:0xf bank_mask:0xf
	v_fmac_f32_dpp v118, v102, v34 row_ror:1 row_mask:0xf bank_mask:0xf
	v_fmac_f32_dpp v119, v103, v35 row_ror:1 row_mask:0xf bank_mask:0xf
	v_fmac_f32_dpp v120, v104, v192 row_ror:1 row_mask:0xf bank_mask:0xf
	v_fmac_f32_dpp v121, v105, v193 row_ror:1 row_mask:0xf bank_mask:0xf
	v_fmac_f32_dpp v122, v106, v194 row_ror:1 row_mask:0xf bank_mask:0xf
	v_fmac_f32_dpp v123, v107, v195 row_ror:1 row_mask:0xf bank_mask:0xf
	v_fmac_f32_dpp v116, v108, v48 row_ror:15 row_mask:0xf bank_mask:0xf
	v_fmac_f32_dpp v117, v109, v49 row_ror:15 row_mask:0xf bank_mask:0xf
	v_fmac_f32_dpp v118, v110, v50 row_ror:15 row_mask:0xf bank_mask:0xf
	v_fmac_f32_dpp v119, v111, v51 row_ror:15 row_mask:0xf bank_mask:0xf
	v_fmac_f32_dpp v120, v112, v200 row_ror:15 row_mask:0xf bank_mask:0xf
	v_fmac_f32_dpp v121, v113, v201 row_ror:15 row_mask:0xf bank_mask:0xf
	v_fmac_f32_dpp v122, v114, v202 row_ror:15 row_mask:0xf bank_mask:0xf
	v_fmac_f32_dpp v123, v115, v203 row_ror:15 row_mask:0xf bank_mask:0xf
	v_mul_f32_e32 v124, 0xbfb8aa3b, v116
	v_mul_f32_e32 v125, 0xbfb8aa3b, v117
	v_mul_f32_e32 v126, 0xbfb8aa3b, v118
	v_mul_f32_e32 v127, 0xbfb8aa3b, v119
	v_exp_f32_e32 v124, v124
	v_exp_f32_e32 v125, v125
	v_exp_f32_e32 v126, v126
	v_exp_f32_e32 v127, v127
	v_add_f32_e32 v124, 1.0, v124
	v_add_f32_e32 v125, 1.0, v125
	v_add_f32_e32 v126, 1.0, v126
	v_add_f32_e32 v127, 1.0, v127
	v_rcp_f32_e32 v124, v124
	v_rcp_f32_e32 v125, v125
	v_rcp_f32_e32 v126, v126
	v_rcp_f32_e32 v127, v127
	v_mul_f32_e32 v116, v116, v124
	v_mul_f32_e32 v117, v117, v125
	v_mul_f32_e32 v118, v118, v126
	v_mul_f32_e32 v119, v119, v127
	v_mul_f32_e32 v116, v116, v120
	v_mul_f32_e32 v117, v117, v121
	v_mul_f32_e32 v118, v118, v122
	v_mul_f32_e32 v119, v119, v123
	v_cvt_pk_bf16_f32 v128, v116, v117
	v_cvt_pk_bf16_f32 v129, v118, v119
	s_mov_b64 s[18:19], exec
	s_andn2_b64 exec, exec, s[16:17]
	global_store_dwordx2 v[140:141], v[128:129], off offset:8
	s_mov_b64 exec, s[18:19]
	s_mov_b64 s[0:1], 0
